# GEMM K-loops: s_setprio 1 ahead of the pre-MMA barrier (redundant lgkmcnt(0) behind it dropped), s_setprio 0 behind the post-MMA barrier; on top of v2
# speedup vs baseline: 1.0065x; 1.0046x over previous
.LBB0_213:
	ds_read_b128 v[146:149], v156
	ds_read_b128 v[150:153], v156 offset:1024
	ds_read_b128 v[160:163], v156 offset:2048
	ds_read_b128 v[164:167], v156 offset:3072
	ds_read_b128 v[168:171], v157
	ds_read_b128 v[172:175], v157 offset:1024
	ds_read_b128 v[176:179], v157 offset:2048
	ds_read_b128 v[180:183], v157 offset:3072
	s_add_u32 s19, s84, 0xfff80080
	s_addc_u32 s20, s85, -1
	s_cmp_eq_u32 s18, 28
	s_cselect_b32 s89, s8, s20
	s_cselect_b32 s88, s9, s19
	s_cselect_b32 s87, s12, s17
	s_cselect_b32 s86, s13, s16
	v_lshl_add_u64 v[216:217], s[84:85], 0, v[138:139]
	s_add_i32 m0, s57, 0xc000
	ds_read_b128 v[184:187], v158
	ds_read_b128 v[188:191], v158 offset:1024
	ds_read_b128 v[192:195], v158 offset:2048
	ds_read_b128 v[196:199], v158 offset:3072
	ds_read_b128 v[200:203], v158 offset:4096
	ds_read_b128 v[204:207], v158 offset:5120
	ds_read_b128 v[208:211], v158 offset:6144
	ds_read_b128 v[212:215], v158 offset:7168
	global_load_lds_dwordx4 v[216:217], off
	v_lshl_add_u64 v[216:217], s[84:85], 0, v[140:141]
	s_add_i32 m0, s57, 0xe000
	s_nop 0
	global_load_lds_dwordx4 v[216:217], off
	s_waitcnt vmcnt(8)
	s_waitcnt lgkmcnt(0)
	s_setprio 1
	s_barrier
	v_mfma_i32_16x16x64_i8 v[126:129], v[146:149], v[184:187], v[126:129]
	v_mfma_i32_16x16x64_i8 v[122:125], v[160:163], v[184:187], v[122:125]
	v_mfma_i32_16x16x64_i8 v[110:113], v[146:149], v[192:195], v[110:113]
	v_mfma_i32_16x16x64_i8 v[106:109], v[160:163], v[192:195], v[106:109]
	v_mfma_i32_16x16x64_i8 v[94:97], v[146:149], v[200:203], v[94:97]
	v_mfma_i32_16x16x64_i8 v[90:93], v[160:163], v[200:203], v[90:93]
	v_mfma_i32_16x16x64_i8 v[78:81], v[146:149], v[208:211], v[78:81]
	v_mfma_i32_16x16x64_i8 v[74:77], v[160:163], v[208:211], v[74:77]
	v_mfma_i32_16x16x64_i8 v[126:129], v[150:153], v[188:191], v[126:129]
	v_mfma_i32_16x16x64_i8 v[122:125], v[164:167], v[188:191], v[122:125]
	v_mfma_i32_16x16x64_i8 v[110:113], v[150:153], v[196:199], v[110:113]
	v_mfma_i32_16x16x64_i8 v[106:109], v[164:167], v[196:199], v[106:109]
	v_mfma_i32_16x16x64_i8 v[94:97], v[150:153], v[204:207], v[94:97]
	v_mfma_i32_16x16x64_i8 v[90:93], v[164:167], v[204:207], v[90:93]
	v_mfma_i32_16x16x64_i8 v[78:81], v[150:153], v[212:215], v[78:81]
	v_mfma_i32_16x16x64_i8 v[74:77], v[164:167], v[212:215], v[74:77]
	s_setprio 0
	s_setprio 1
	v_mfma_i32_16x16x64_i8 v[118:121], v[168:171], v[184:187], v[118:121]
	v_mfma_i32_16x16x64_i8 v[114:117], v[176:179], v[184:187], v[114:117]
	v_mfma_i32_16x16x64_i8 v[102:105], v[168:171], v[192:195], v[102:105]
	v_mfma_i32_16x16x64_i8 v[98:101], v[176:179], v[192:195], v[98:101]
	v_mfma_i32_16x16x64_i8 v[86:89], v[168:171], v[200:203], v[86:89]
	v_mfma_i32_16x16x64_i8 v[82:85], v[176:179], v[200:203], v[82:85]
	v_mfma_i32_16x16x64_i8 v[70:73], v[168:171], v[208:211], v[70:73]
	v_mfma_i32_16x16x64_i8 v[66:69], v[176:179], v[208:211], v[66:69]
	v_mfma_i32_16x16x64_i8 v[118:121], v[172:175], v[188:191], v[118:121]
	v_mfma_i32_16x16x64_i8 v[114:117], v[180:183], v[188:191], v[114:117]
	v_mfma_i32_16x16x64_i8 v[102:105], v[172:175], v[196:199], v[102:105]
	v_mfma_i32_16x16x64_i8 v[98:101], v[180:183], v[196:199], v[98:101]
	v_mfma_i32_16x16x64_i8 v[86:89], v[172:175], v[204:207], v[86:89]
	v_mfma_i32_16x16x64_i8 v[82:85], v[180:183], v[204:207], v[82:85]
	v_mfma_i32_16x16x64_i8 v[70:73], v[172:175], v[212:215], v[70:73]
	v_mfma_i32_16x16x64_i8 v[66:69], v[180:183], v[212:215], v[66:69]
	s_barrier
	s_setprio 0
	s_add_i32 s19, s83, s35
	v_lshl_add_u64 v[216:217], s[86:87], 0, v[134:135]
	s_mov_b32 m0, s19
	ds_read_b128 v[184:187], v158 offset:16384
	ds_read_b128 v[188:191], v158 offset:17408
	ds_read_b128 v[192:195], v158 offset:18432
	ds_read_b128 v[196:199], v158 offset:19456
	ds_read_b128 v[200:203], v158 offset:20480
	ds_read_b128 v[204:207], v158 offset:21504
	ds_read_b128 v[208:211], v158 offset:22528
	ds_read_b128 v[212:215], v158 offset:23552
	global_load_lds_dwordx4 v[216:217], off
	s_add_i32 m0, s19, 0x2000
	s_add_u32 s20, s86, 0x80000
	v_lshl_add_u64 v[218:219], s[86:87], 0, v[130:131]
	s_addc_u32 s21, s87, 0
	s_add_i32 s19, s90, s35
	global_load_lds_dwordx4 v[218:219], off
	v_lshl_add_u64 v[220:221], s[20:21], 0, v[134:135]
	s_mov_b32 m0, s19
	v_lshl_add_u64 v[222:223], s[88:89], 0, v[132:133]
	global_load_lds_dwordx4 v[220:221], off
	v_lshl_add_u64 v[220:221], s[20:21], 0, v[130:131]
	s_add_i32 m0, s19, 0x2000
	s_nop 0
	global_load_lds_dwordx4 v[220:221], off
	v_lshl_add_u64 v[220:221], s[88:89], 0, v[136:137]
	s_mov_b32 m0, s57
	s_nop 0
	global_load_lds_dwordx4 v[220:221], off
	s_mov_b32 m0, s58
	s_nop 0
	global_load_lds_dwordx4 v[222:223], off
	s_waitcnt vmcnt(8)
	s_waitcnt lgkmcnt(0)
	s_setprio 1
	s_barrier
	v_mfma_i32_16x16x64_i8 v[62:65], v[146:149], v[184:187], v[62:65]
	v_mfma_i32_16x16x64_i8 v[58:61], v[160:163], v[184:187], v[58:61]
	v_mfma_i32_16x16x64_i8 v[46:49], v[146:149], v[192:195], v[46:49]
	v_mfma_i32_16x16x64_i8 v[42:45], v[160:163], v[192:195], v[42:45]
	v_mfma_i32_16x16x64_i8 v[30:33], v[146:149], v[200:203], v[30:33]
	v_mfma_i32_16x16x64_i8 v[26:29], v[160:163], v[200:203], v[26:29]
	v_mfma_i32_16x16x64_i8 v[14:17], v[146:149], v[208:211], v[14:17]
	v_mfma_i32_16x16x64_i8 v[10:13], v[160:163], v[208:211], v[10:13]
	v_mfma_i32_16x16x64_i8 v[62:65], v[150:153], v[188:191], v[62:65]
	v_mfma_i32_16x16x64_i8 v[58:61], v[164:167], v[188:191], v[58:61]
	v_mfma_i32_16x16x64_i8 v[46:49], v[150:153], v[196:199], v[46:49]
	v_mfma_i32_16x16x64_i8 v[42:45], v[164:167], v[196:199], v[42:45]
	v_mfma_i32_16x16x64_i8 v[30:33], v[150:153], v[204:207], v[30:33]
	v_mfma_i32_16x16x64_i8 v[26:29], v[164:167], v[204:207], v[26:29]
	v_mfma_i32_16x16x64_i8 v[14:17], v[150:153], v[212:215], v[14:17]
	v_mfma_i32_16x16x64_i8 v[10:13], v[164:167], v[212:215], v[10:13]
	s_setprio 0
	s_setprio 1
	v_mfma_i32_16x16x64_i8 v[54:57], v[168:171], v[184:187], v[54:57]
	v_mfma_i32_16x16x64_i8 v[50:53], v[176:179], v[184:187], v[50:53]
	v_mfma_i32_16x16x64_i8 v[38:41], v[168:171], v[192:195], v[38:41]
	v_mfma_i32_16x16x64_i8 v[34:37], v[176:179], v[192:195], v[34:37]
	v_mfma_i32_16x16x64_i8 v[22:25], v[168:171], v[200:203], v[22:25]
	v_mfma_i32_16x16x64_i8 v[18:21], v[176:179], v[200:203], v[18:21]
	v_mfma_i32_16x16x64_i8 v[6:9], v[168:171], v[208:211], v[6:9]
	v_mfma_i32_16x16x64_i8 v[2:5], v[176:179], v[208:211], v[2:5]
	v_mfma_i32_16x16x64_i8 v[54:57], v[172:175], v[188:191], v[54:57]
	v_mfma_i32_16x16x64_i8 v[50:53], v[180:183], v[188:191], v[50:53]
	v_mfma_i32_16x16x64_i8 v[38:41], v[172:175], v[196:199], v[38:41]
	v_mfma_i32_16x16x64_i8 v[34:37], v[180:183], v[196:199], v[34:37]
	v_mfma_i32_16x16x64_i8 v[22:25], v[172:175], v[204:207], v[22:25]
	v_mfma_i32_16x16x64_i8 v[18:21], v[180:183], v[204:207], v[18:21]
	v_mfma_i32_16x16x64_i8 v[6:9], v[172:175], v[212:215], v[6:9]
	v_mfma_i32_16x16x64_i8 v[2:5], v[180:183], v[212:215], v[2:5]
	s_barrier
	s_setprio 0
	s_add_i32 s19, 0, 0x18000
	v_add_u32_e32 v159, s19, v154
	s_add_i32 s22, 0, 0x1c000
	ds_read_b128 v[146:149], v159
	ds_read_b128 v[150:153], v159 offset:1024
	ds_read_b128 v[160:163], v159 offset:2048
	ds_read_b128 v[164:167], v159 offset:3072
	v_add_u32_e32 v159, s22, v154
	ds_read_b128 v[168:171], v159
	ds_read_b128 v[172:175], v159 offset:1024
	ds_read_b128 v[176:179], v159 offset:2048
	ds_read_b128 v[180:183], v159 offset:3072
	s_add_u32 s20, s88, 0x80000
	s_addc_u32 s21, s89, 0
	s_mov_b32 m0, s59
	v_lshl_add_u64 v[224:225], s[20:21], 0, v[136:137]
	ds_read_b128 v[184:187], v158 offset:32768
	ds_read_b128 v[188:191], v158 offset:33792
	ds_read_b128 v[192:195], v158 offset:34816
	ds_read_b128 v[196:199], v158 offset:35840
	ds_read_b128 v[200:203], v158 offset:36864
	ds_read_b128 v[204:207], v158 offset:37888
	ds_read_b128 v[208:211], v158 offset:38912
	ds_read_b128 v[212:215], v158 offset:39936
	global_load_lds_dwordx4 v[224:225], off
	v_lshl_add_u64 v[224:225], s[20:21], 0, v[132:133]
	s_mov_b32 m0, s61
	s_nop 0
	global_load_lds_dwordx4 v[224:225], off
	s_waitcnt vmcnt(8)
	s_waitcnt lgkmcnt(0)
	s_setprio 1
	s_barrier
	v_mfma_i32_16x16x64_i8 v[126:129], v[146:149], v[184:187], v[126:129]
	v_mfma_i32_16x16x64_i8 v[122:125], v[160:163], v[184:187], v[122:125]
	v_mfma_i32_16x16x64_i8 v[110:113], v[146:149], v[192:195], v[110:113]
	v_mfma_i32_16x16x64_i8 v[106:109], v[160:163], v[192:195], v[106:109]
	v_mfma_i32_16x16x64_i8 v[94:97], v[146:149], v[200:203], v[94:97]
	v_mfma_i32_16x16x64_i8 v[90:93], v[160:163], v[200:203], v[90:93]
	v_mfma_i32_16x16x64_i8 v[78:81], v[146:149], v[208:211], v[78:81]
	v_mfma_i32_16x16x64_i8 v[74:77], v[160:163], v[208:211], v[74:77]
	v_mfma_i32_16x16x64_i8 v[126:129], v[150:153], v[188:191], v[126:129]
	v_mfma_i32_16x16x64_i8 v[122:125], v[164:167], v[188:191], v[122:125]
	v_mfma_i32_16x16x64_i8 v[110:113], v[150:153], v[196:199], v[110:113]
	v_mfma_i32_16x16x64_i8 v[106:109], v[164:167], v[196:199], v[106:109]
	v_mfma_i32_16x16x64_i8 v[94:97], v[150:153], v[204:207], v[94:97]
	v_mfma_i32_16x16x64_i8 v[90:93], v[164:167], v[204:207], v[90:93]
	v_mfma_i32_16x16x64_i8 v[78:81], v[150:153], v[212:215], v[78:81]
	v_mfma_i32_16x16x64_i8 v[74:77], v[164:167], v[212:215], v[74:77]
	s_setprio 0
	s_setprio 1
	v_mfma_i32_16x16x64_i8 v[118:121], v[168:171], v[184:187], v[118:121]
	v_mfma_i32_16x16x64_i8 v[114:117], v[176:179], v[184:187], v[114:117]
	v_mfma_i32_16x16x64_i8 v[102:105], v[168:171], v[192:195], v[102:105]
	v_mfma_i32_16x16x64_i8 v[98:101], v[176:179], v[192:195], v[98:101]
	v_mfma_i32_16x16x64_i8 v[86:89], v[168:171], v[200:203], v[86:89]
	v_mfma_i32_16x16x64_i8 v[82:85], v[176:179], v[200:203], v[82:85]
	v_mfma_i32_16x16x64_i8 v[70:73], v[168:171], v[208:211], v[70:73]
	v_mfma_i32_16x16x64_i8 v[66:69], v[176:179], v[208:211], v[66:69]
	v_mfma_i32_16x16x64_i8 v[118:121], v[172:175], v[188:191], v[118:121]
	v_mfma_i32_16x16x64_i8 v[114:117], v[180:183], v[188:191], v[114:117]
	v_mfma_i32_16x16x64_i8 v[102:105], v[172:175], v[196:199], v[102:105]
	v_mfma_i32_16x16x64_i8 v[98:101], v[180:183], v[196:199], v[98:101]
	v_mfma_i32_16x16x64_i8 v[86:89], v[172:175], v[204:207], v[86:89]
	v_mfma_i32_16x16x64_i8 v[82:85], v[180:183], v[204:207], v[82:85]
	v_mfma_i32_16x16x64_i8 v[70:73], v[172:175], v[212:215], v[70:73]
	v_mfma_i32_16x16x64_i8 v[66:69], v[180:183], v[212:215], v[66:69]
	s_barrier
	s_setprio 0
	s_add_i32 s19, s19, s35
	v_lshl_add_u64 v[216:217], v[216:217], 0, s[4:5]
	s_mov_b32 m0, s19
	ds_read_b128 v[184:187], v158 offset:49152
	ds_read_b128 v[188:191], v158 offset:50176
	ds_read_b128 v[192:195], v158 offset:51200
	ds_read_b128 v[196:199], v158 offset:52224
	ds_read_b128 v[200:203], v158 offset:53248
	ds_read_b128 v[204:207], v158 offset:54272
	ds_read_b128 v[208:211], v158 offset:55296
	ds_read_b128 v[212:215], v158 offset:56320
	global_load_lds_dwordx4 v[216:217], off
	s_add_i32 m0, s19, 0x2000
	s_add_u32 s20, s86, 0x80080
	v_lshl_add_u64 v[216:217], v[218:219], 0, s[4:5]
	s_addc_u32 s21, s87, 0
	s_add_i32 s19, s22, s35
	global_load_lds_dwordx4 v[216:217], off
	v_lshl_add_u64 v[216:217], s[20:21], 0, v[134:135]
	s_mov_b32 m0, s19
	s_nop 0
	global_load_lds_dwordx4 v[216:217], off
	v_lshl_add_u64 v[216:217], s[20:21], 0, v[130:131]
	s_add_i32 m0, s19, 0x2000
	s_nop 0
	global_load_lds_dwordx4 v[216:217], off
	v_lshl_add_u64 v[216:217], v[220:221], 0, s[4:5]
	s_mov_b32 m0, s67
	s_nop 0
	global_load_lds_dwordx4 v[216:217], off
	v_lshl_add_u64 v[216:217], v[222:223], 0, s[4:5]
	s_mov_b32 m0, s68
	s_nop 0
	global_load_lds_dwordx4 v[216:217], off
	s_waitcnt vmcnt(8)
	s_waitcnt lgkmcnt(0)
	s_setprio 1
	s_barrier
	v_mfma_i32_16x16x64_i8 v[62:65], v[146:149], v[184:187], v[62:65]
	v_mfma_i32_16x16x64_i8 v[58:61], v[160:163], v[184:187], v[58:61]
	v_mfma_i32_16x16x64_i8 v[46:49], v[146:149], v[192:195], v[46:49]
	v_mfma_i32_16x16x64_i8 v[42:45], v[160:163], v[192:195], v[42:45]
	v_mfma_i32_16x16x64_i8 v[30:33], v[146:149], v[200:203], v[30:33]
	v_mfma_i32_16x16x64_i8 v[26:29], v[160:163], v[200:203], v[26:29]
	v_mfma_i32_16x16x64_i8 v[14:17], v[146:149], v[208:211], v[14:17]
	v_mfma_i32_16x16x64_i8 v[10:13], v[160:163], v[208:211], v[10:13]
	v_mfma_i32_16x16x64_i8 v[62:65], v[150:153], v[188:191], v[62:65]
	v_mfma_i32_16x16x64_i8 v[58:61], v[164:167], v[188:191], v[58:61]
	v_mfma_i32_16x16x64_i8 v[46:49], v[150:153], v[196:199], v[46:49]
	v_mfma_i32_16x16x64_i8 v[42:45], v[164:167], v[196:199], v[42:45]
	v_mfma_i32_16x16x64_i8 v[30:33], v[150:153], v[204:207], v[30:33]
	v_mfma_i32_16x16x64_i8 v[26:29], v[164:167], v[204:207], v[26:29]
	v_mfma_i32_16x16x64_i8 v[14:17], v[150:153], v[212:215], v[14:17]
	v_mfma_i32_16x16x64_i8 v[10:13], v[164:167], v[212:215], v[10:13]
	s_setprio 0
	s_setprio 1
	v_mfma_i32_16x16x64_i8 v[54:57], v[168:171], v[184:187], v[54:57]
	v_mfma_i32_16x16x64_i8 v[50:53], v[176:179], v[184:187], v[50:53]
	v_mfma_i32_16x16x64_i8 v[38:41], v[168:171], v[192:195], v[38:41]
	v_mfma_i32_16x16x64_i8 v[34:37], v[176:179], v[192:195], v[34:37]
	v_mfma_i32_16x16x64_i8 v[22:25], v[168:171], v[200:203], v[22:25]
	v_mfma_i32_16x16x64_i8 v[18:21], v[176:179], v[200:203], v[18:21]
	v_mfma_i32_16x16x64_i8 v[6:9], v[168:171], v[208:211], v[6:9]
	v_mfma_i32_16x16x64_i8 v[2:5], v[176:179], v[208:211], v[2:5]
	v_mfma_i32_16x16x64_i8 v[54:57], v[172:175], v[188:191], v[54:57]
	v_mfma_i32_16x16x64_i8 v[50:53], v[180:183], v[188:191], v[50:53]
	v_mfma_i32_16x16x64_i8 v[38:41], v[172:175], v[196:199], v[38:41]
	v_mfma_i32_16x16x64_i8 v[34:37], v[180:183], v[196:199], v[34:37]
	v_mfma_i32_16x16x64_i8 v[22:25], v[172:175], v[204:207], v[22:25]
	v_mfma_i32_16x16x64_i8 v[18:21], v[180:183], v[204:207], v[18:21]
	v_mfma_i32_16x16x64_i8 v[6:9], v[172:175], v[212:215], v[6:9]
	v_mfma_i32_16x16x64_i8 v[2:5], v[180:183], v[212:215], v[2:5]
	s_barrier
	s_setprio 0
	s_add_i32 s18, s18, 2
	s_add_u32 s84, s84, 0x100
	s_addc_u32 s85, s85, 0
	s_add_u32 s16, s16, 0x100
	s_addc_u32 s17, s17, 0
	s_cmp_gt_u32 s18, 29
	s_cbranch_scc0 .LBB0_213
	s_and_b64 vcc, exec, s[6:7]
	s_cbranch_vccz .LBB0_216
	s_barrier

.LBB0_362:
	ds_read_b128 v[106:109], v168
	ds_read_b128 v[110:113], v168 offset:1024
	ds_read_b128 v[114:117], v168 offset:2048
	ds_read_b128 v[122:125], v168 offset:3072
	ds_read_b128 v[160:163], v169
	ds_read_b128 v[172:175], v169 offset:1024
	ds_read_b128 v[176:179], v169 offset:2048
	ds_read_b128 v[180:183], v169 offset:3072
	s_add_u32 s16, s6, 0xffea8080
	s_addc_u32 s17, s7, -1
	s_cmpk_eq_i32 s13, 0x52
	s_cselect_b32 s85, s51, s17
	s_cselect_b32 s84, s50, s16
	s_cselect_b32 s83, s81, s12
	s_cselect_b32 s82, s80, s8
	v_lshl_add_u64 v[216:217], s[6:7], 0, v[154:155]
	s_add_i32 m0, s56, 0xc000
	ds_read_b128 v[184:187], v170
	ds_read_b128 v[188:191], v170 offset:1024
	ds_read_b128 v[192:195], v170 offset:2048
	ds_read_b128 v[196:199], v170 offset:3072
	ds_read_b128 v[200:203], v170 offset:4096
	ds_read_b128 v[204:207], v170 offset:5120
	ds_read_b128 v[208:211], v170 offset:6144
	ds_read_b128 v[212:215], v170 offset:7168
	global_load_lds_dwordx4 v[216:217], off
	v_lshl_add_u64 v[216:217], s[6:7], 0, v[156:157]
	s_add_i32 m0, s56, 0xe000
	s_nop 0
	global_load_lds_dwordx4 v[216:217], off
	s_waitcnt vmcnt(8)
	s_waitcnt lgkmcnt(0)
	s_setprio 1
	s_barrier
	v_mfma_i32_16x16x64_i8 v[142:145], v[106:109], v[184:187], v[142:145]
	v_mfma_i32_16x16x64_i8 v[138:141], v[114:117], v[184:187], v[138:141]
	v_mfma_i32_16x16x64_i8 v[126:129], v[106:109], v[192:195], v[126:129]
	v_mfma_i32_16x16x64_i8 v[118:121], v[114:117], v[192:195], v[118:121]
	v_mfma_i32_16x16x64_i8 v[94:97], v[106:109], v[200:203], v[94:97]
	v_mfma_i32_16x16x64_i8 v[90:93], v[114:117], v[200:203], v[90:93]
	v_mfma_i32_16x16x64_i8 v[78:81], v[106:109], v[208:211], v[78:81]
	v_mfma_i32_16x16x64_i8 v[74:77], v[114:117], v[208:211], v[74:77]
	v_mfma_i32_16x16x64_i8 v[142:145], v[110:113], v[188:191], v[142:145]
	v_mfma_i32_16x16x64_i8 v[138:141], v[122:125], v[188:191], v[138:141]
	v_mfma_i32_16x16x64_i8 v[126:129], v[110:113], v[196:199], v[126:129]
	v_mfma_i32_16x16x64_i8 v[118:121], v[122:125], v[196:199], v[118:121]
	v_mfma_i32_16x16x64_i8 v[94:97], v[110:113], v[204:207], v[94:97]
	v_mfma_i32_16x16x64_i8 v[90:93], v[122:125], v[204:207], v[90:93]
	v_mfma_i32_16x16x64_i8 v[78:81], v[110:113], v[212:215], v[78:81]
	v_mfma_i32_16x16x64_i8 v[74:77], v[122:125], v[212:215], v[74:77]
	s_setprio 0
	s_setprio 1
	v_mfma_i32_16x16x64_i8 v[134:137], v[160:163], v[184:187], v[134:137]
	v_mfma_i32_16x16x64_i8 v[130:133], v[176:179], v[184:187], v[130:133]
	v_mfma_i32_16x16x64_i8 v[102:105], v[160:163], v[192:195], v[102:105]
	v_mfma_i32_16x16x64_i8 v[98:101], v[176:179], v[192:195], v[98:101]
	v_mfma_i32_16x16x64_i8 v[86:89], v[160:163], v[200:203], v[86:89]
	v_mfma_i32_16x16x64_i8 v[82:85], v[176:179], v[200:203], v[82:85]
	v_mfma_i32_16x16x64_i8 v[70:73], v[160:163], v[208:211], v[70:73]
	v_mfma_i32_16x16x64_i8 v[66:69], v[176:179], v[208:211], v[66:69]
	v_mfma_i32_16x16x64_i8 v[134:137], v[172:175], v[188:191], v[134:137]
	v_mfma_i32_16x16x64_i8 v[130:133], v[180:183], v[188:191], v[130:133]
	v_mfma_i32_16x16x64_i8 v[102:105], v[172:175], v[196:199], v[102:105]
	v_mfma_i32_16x16x64_i8 v[98:101], v[180:183], v[196:199], v[98:101]
	v_mfma_i32_16x16x64_i8 v[86:89], v[172:175], v[204:207], v[86:89]
	v_mfma_i32_16x16x64_i8 v[82:85], v[180:183], v[204:207], v[82:85]
	v_mfma_i32_16x16x64_i8 v[70:73], v[172:175], v[212:215], v[70:73]
	v_mfma_i32_16x16x64_i8 v[66:69], v[180:183], v[212:215], v[66:69]
	s_barrier
	s_setprio 0
	s_add_i32 s16, s87, s35
	v_lshl_add_u64 v[216:217], s[82:83], 0, v[148:149]
	s_mov_b32 m0, s16
	ds_read_b128 v[184:187], v170 offset:16384
	ds_read_b128 v[188:191], v170 offset:17408
	ds_read_b128 v[192:195], v170 offset:18432
	ds_read_b128 v[196:199], v170 offset:19456
	ds_read_b128 v[200:203], v170 offset:20480
	ds_read_b128 v[204:207], v170 offset:21504
	ds_read_b128 v[208:211], v170 offset:22528
	ds_read_b128 v[212:215], v170 offset:23552
	global_load_lds_dwordx4 v[216:217], off
	s_add_i32 m0, s16, 0x2000
	s_add_u32 s16, s82, 0x158000
	v_lshl_add_u64 v[218:219], s[82:83], 0, v[152:153]
	s_addc_u32 s17, s83, 0
	s_add_i32 s18, s88, s35
	global_load_lds_dwordx4 v[218:219], off
	v_lshl_add_u64 v[220:221], s[16:17], 0, v[148:149]
	s_mov_b32 m0, s18
	v_lshl_add_u64 v[222:223], s[84:85], 0, v[150:151]
	global_load_lds_dwordx4 v[220:221], off
	v_lshl_add_u64 v[220:221], s[16:17], 0, v[152:153]
	s_add_i32 m0, s18, 0x2000
	s_nop 0
	global_load_lds_dwordx4 v[220:221], off
	v_lshl_add_u64 v[220:221], s[84:85], 0, v[146:147]
	s_mov_b32 m0, s56
	s_nop 0
	global_load_lds_dwordx4 v[220:221], off
	s_mov_b32 m0, s57
	s_nop 0
	global_load_lds_dwordx4 v[222:223], off
	s_waitcnt vmcnt(8)
	s_waitcnt lgkmcnt(0)
	s_setprio 1
	s_barrier
	v_mfma_i32_16x16x64_i8 v[62:65], v[106:109], v[184:187], v[62:65]
	v_mfma_i32_16x16x64_i8 v[58:61], v[114:117], v[184:187], v[58:61]
	v_mfma_i32_16x16x64_i8 v[46:49], v[106:109], v[192:195], v[46:49]
	v_mfma_i32_16x16x64_i8 v[42:45], v[114:117], v[192:195], v[42:45]
	v_mfma_i32_16x16x64_i8 v[30:33], v[106:109], v[200:203], v[30:33]
	v_mfma_i32_16x16x64_i8 v[26:29], v[114:117], v[200:203], v[26:29]
	v_mfma_i32_16x16x64_i8 v[14:17], v[106:109], v[208:211], v[14:17]
	v_mfma_i32_16x16x64_i8 v[10:13], v[114:117], v[208:211], v[10:13]
	v_mfma_i32_16x16x64_i8 v[62:65], v[110:113], v[188:191], v[62:65]
	v_mfma_i32_16x16x64_i8 v[58:61], v[122:125], v[188:191], v[58:61]
	v_mfma_i32_16x16x64_i8 v[46:49], v[110:113], v[196:199], v[46:49]
	v_mfma_i32_16x16x64_i8 v[42:45], v[122:125], v[196:199], v[42:45]
	v_mfma_i32_16x16x64_i8 v[30:33], v[110:113], v[204:207], v[30:33]
	v_mfma_i32_16x16x64_i8 v[26:29], v[122:125], v[204:207], v[26:29]
	v_mfma_i32_16x16x64_i8 v[14:17], v[110:113], v[212:215], v[14:17]
	v_mfma_i32_16x16x64_i8 v[10:13], v[122:125], v[212:215], v[10:13]
	s_setprio 0
	s_setprio 1
	v_mfma_i32_16x16x64_i8 v[54:57], v[160:163], v[184:187], v[54:57]
	v_mfma_i32_16x16x64_i8 v[50:53], v[176:179], v[184:187], v[50:53]
	v_mfma_i32_16x16x64_i8 v[38:41], v[160:163], v[192:195], v[38:41]
	v_mfma_i32_16x16x64_i8 v[34:37], v[176:179], v[192:195], v[34:37]
	v_mfma_i32_16x16x64_i8 v[22:25], v[160:163], v[200:203], v[22:25]
	v_mfma_i32_16x16x64_i8 v[18:21], v[176:179], v[200:203], v[18:21]
	v_mfma_i32_16x16x64_i8 v[6:9], v[160:163], v[208:211], v[6:9]
	v_mfma_i32_16x16x64_i8 v[2:5], v[176:179], v[208:211], v[2:5]
	v_mfma_i32_16x16x64_i8 v[54:57], v[172:175], v[188:191], v[54:57]
	v_mfma_i32_16x16x64_i8 v[50:53], v[180:183], v[188:191], v[50:53]
	v_mfma_i32_16x16x64_i8 v[38:41], v[172:175], v[196:199], v[38:41]
	v_mfma_i32_16x16x64_i8 v[34:37], v[180:183], v[196:199], v[34:37]
	v_mfma_i32_16x16x64_i8 v[22:25], v[172:175], v[204:207], v[22:25]
	v_mfma_i32_16x16x64_i8 v[18:21], v[180:183], v[204:207], v[18:21]
	v_mfma_i32_16x16x64_i8 v[6:9], v[172:175], v[212:215], v[6:9]
	v_mfma_i32_16x16x64_i8 v[2:5], v[180:183], v[212:215], v[2:5]
	s_barrier
	s_setprio 0
	s_add_i32 s18, 0, 0x18000
	s_add_i32 s19, 0, 0x1c000
	v_add_u32_e32 v122, s18, v165
	v_add_u32_e32 v164, s19, v165
	ds_read_b128 v[106:109], v122
	ds_read_b128 v[110:113], v122 offset:1024
	ds_read_b128 v[114:117], v122 offset:2048
	ds_read_b128 v[122:125], v122 offset:3072
	ds_read_b128 v[160:163], v164
	ds_read_b128 v[172:175], v164 offset:1024
	ds_read_b128 v[176:179], v164 offset:2048
	ds_read_b128 v[180:183], v164 offset:3072
	s_add_u32 s16, s84, 0x158000
	s_addc_u32 s17, s85, 0
	s_mov_b32 m0, s58
	v_lshl_add_u64 v[224:225], s[16:17], 0, v[146:147]
	ds_read_b128 v[184:187], v170 offset:32768
	ds_read_b128 v[188:191], v170 offset:33792
	ds_read_b128 v[192:195], v170 offset:34816
	ds_read_b128 v[196:199], v170 offset:35840
	ds_read_b128 v[200:203], v170 offset:36864
	ds_read_b128 v[204:207], v170 offset:37888
	ds_read_b128 v[208:211], v170 offset:38912
	ds_read_b128 v[212:215], v170 offset:39936
	global_load_lds_dwordx4 v[224:225], off
	v_lshl_add_u64 v[224:225], s[16:17], 0, v[150:151]
	s_mov_b32 m0, s59
	s_nop 0
	global_load_lds_dwordx4 v[224:225], off
	s_waitcnt vmcnt(8)
	s_waitcnt lgkmcnt(0)
	s_setprio 1
	s_barrier
	v_mfma_i32_16x16x64_i8 v[142:145], v[106:109], v[184:187], v[142:145]
	v_mfma_i32_16x16x64_i8 v[138:141], v[114:117], v[184:187], v[138:141]
	v_mfma_i32_16x16x64_i8 v[126:129], v[106:109], v[192:195], v[126:129]
	v_mfma_i32_16x16x64_i8 v[118:121], v[114:117], v[192:195], v[118:121]
	v_mfma_i32_16x16x64_i8 v[94:97], v[106:109], v[200:203], v[94:97]
	v_mfma_i32_16x16x64_i8 v[90:93], v[114:117], v[200:203], v[90:93]
	v_mfma_i32_16x16x64_i8 v[78:81], v[106:109], v[208:211], v[78:81]
	v_mfma_i32_16x16x64_i8 v[74:77], v[114:117], v[208:211], v[74:77]
	v_mfma_i32_16x16x64_i8 v[142:145], v[110:113], v[188:191], v[142:145]
	v_mfma_i32_16x16x64_i8 v[138:141], v[122:125], v[188:191], v[138:141]
	v_mfma_i32_16x16x64_i8 v[126:129], v[110:113], v[196:199], v[126:129]
	v_mfma_i32_16x16x64_i8 v[118:121], v[122:125], v[196:199], v[118:121]
	v_mfma_i32_16x16x64_i8 v[94:97], v[110:113], v[204:207], v[94:97]
	v_mfma_i32_16x16x64_i8 v[90:93], v[122:125], v[204:207], v[90:93]
	v_mfma_i32_16x16x64_i8 v[78:81], v[110:113], v[212:215], v[78:81]
	v_mfma_i32_16x16x64_i8 v[74:77], v[122:125], v[212:215], v[74:77]
	s_setprio 0
	s_setprio 1
	v_mfma_i32_16x16x64_i8 v[134:137], v[160:163], v[184:187], v[134:137]
	v_mfma_i32_16x16x64_i8 v[130:133], v[176:179], v[184:187], v[130:133]
	v_mfma_i32_16x16x64_i8 v[102:105], v[160:163], v[192:195], v[102:105]
	v_mfma_i32_16x16x64_i8 v[98:101], v[176:179], v[192:195], v[98:101]
	v_mfma_i32_16x16x64_i8 v[86:89], v[160:163], v[200:203], v[86:89]
	v_mfma_i32_16x16x64_i8 v[82:85], v[176:179], v[200:203], v[82:85]
	v_mfma_i32_16x16x64_i8 v[70:73], v[160:163], v[208:211], v[70:73]
	v_mfma_i32_16x16x64_i8 v[66:69], v[176:179], v[208:211], v[66:69]
	v_mfma_i32_16x16x64_i8 v[134:137], v[172:175], v[188:191], v[134:137]
	v_mfma_i32_16x16x64_i8 v[130:133], v[180:183], v[188:191], v[130:133]
	v_mfma_i32_16x16x64_i8 v[102:105], v[172:175], v[196:199], v[102:105]
	v_mfma_i32_16x16x64_i8 v[98:101], v[180:183], v[196:199], v[98:101]
	v_mfma_i32_16x16x64_i8 v[86:89], v[172:175], v[204:207], v[86:89]
	v_mfma_i32_16x16x64_i8 v[82:85], v[180:183], v[204:207], v[82:85]
	v_mfma_i32_16x16x64_i8 v[70:73], v[172:175], v[212:215], v[70:73]
	v_mfma_i32_16x16x64_i8 v[66:69], v[180:183], v[212:215], v[66:69]
	s_barrier
	s_setprio 0
	s_add_i32 s16, s18, s35
	v_lshl_add_u64 v[216:217], v[216:217], 0, s[44:45]
	s_mov_b32 m0, s16
	ds_read_b128 v[184:187], v170 offset:49152
	ds_read_b128 v[188:191], v170 offset:50176
	ds_read_b128 v[192:195], v170 offset:51200
	ds_read_b128 v[196:199], v170 offset:52224
	ds_read_b128 v[200:203], v170 offset:53248
	ds_read_b128 v[204:207], v170 offset:54272
	ds_read_b128 v[208:211], v170 offset:55296
	ds_read_b128 v[212:215], v170 offset:56320
	global_load_lds_dwordx4 v[216:217], off
	s_add_i32 m0, s16, 0x2000
	s_add_u32 s16, s82, 0x158080
	v_lshl_add_u64 v[216:217], v[218:219], 0, s[44:45]
	s_addc_u32 s17, s83, 0
	s_add_i32 s18, s19, s35
	global_load_lds_dwordx4 v[216:217], off
	v_lshl_add_u64 v[216:217], s[16:17], 0, v[148:149]
	s_mov_b32 m0, s18
	s_nop 0
	global_load_lds_dwordx4 v[216:217], off
	v_lshl_add_u64 v[216:217], s[16:17], 0, v[152:153]
	s_add_i32 m0, s18, 0x2000
	s_nop 0
	global_load_lds_dwordx4 v[216:217], off
	v_lshl_add_u64 v[216:217], v[220:221], 0, s[44:45]
	s_mov_b32 m0, s61
	s_nop 0
	global_load_lds_dwordx4 v[216:217], off
	v_lshl_add_u64 v[216:217], v[222:223], 0, s[44:45]
	s_mov_b32 m0, s66
	s_nop 0
	global_load_lds_dwordx4 v[216:217], off
	s_waitcnt vmcnt(8)
	s_waitcnt lgkmcnt(0)
	s_setprio 1
	s_barrier
	v_mfma_i32_16x16x64_i8 v[62:65], v[106:109], v[184:187], v[62:65]
	v_mfma_i32_16x16x64_i8 v[58:61], v[114:117], v[184:187], v[58:61]
	v_mfma_i32_16x16x64_i8 v[46:49], v[106:109], v[192:195], v[46:49]
	v_mfma_i32_16x16x64_i8 v[42:45], v[114:117], v[192:195], v[42:45]
	v_mfma_i32_16x16x64_i8 v[30:33], v[106:109], v[200:203], v[30:33]
	v_mfma_i32_16x16x64_i8 v[26:29], v[114:117], v[200:203], v[26:29]
	v_mfma_i32_16x16x64_i8 v[14:17], v[106:109], v[208:211], v[14:17]
	v_mfma_i32_16x16x64_i8 v[10:13], v[114:117], v[208:211], v[10:13]
	v_mfma_i32_16x16x64_i8 v[62:65], v[110:113], v[188:191], v[62:65]
	v_mfma_i32_16x16x64_i8 v[58:61], v[122:125], v[188:191], v[58:61]
	v_mfma_i32_16x16x64_i8 v[46:49], v[110:113], v[196:199], v[46:49]
	v_mfma_i32_16x16x64_i8 v[42:45], v[122:125], v[196:199], v[42:45]
	v_mfma_i32_16x16x64_i8 v[30:33], v[110:113], v[204:207], v[30:33]
	v_mfma_i32_16x16x64_i8 v[26:29], v[122:125], v[204:207], v[26:29]
	v_mfma_i32_16x16x64_i8 v[14:17], v[110:113], v[212:215], v[14:17]
	v_mfma_i32_16x16x64_i8 v[10:13], v[122:125], v[212:215], v[10:13]
	s_setprio 0
	s_setprio 1
	v_mfma_i32_16x16x64_i8 v[54:57], v[160:163], v[184:187], v[54:57]
	v_mfma_i32_16x16x64_i8 v[50:53], v[176:179], v[184:187], v[50:53]
	v_mfma_i32_16x16x64_i8 v[38:41], v[160:163], v[192:195], v[38:41]
	v_mfma_i32_16x16x64_i8 v[34:37], v[176:179], v[192:195], v[34:37]
	v_mfma_i32_16x16x64_i8 v[22:25], v[160:163], v[200:203], v[22:25]
	v_mfma_i32_16x16x64_i8 v[18:21], v[176:179], v[200:203], v[18:21]
	v_mfma_i32_16x16x64_i8 v[6:9], v[160:163], v[208:211], v[6:9]
	v_mfma_i32_16x16x64_i8 v[2:5], v[176:179], v[208:211], v[2:5]
	v_mfma_i32_16x16x64_i8 v[54:57], v[172:175], v[188:191], v[54:57]
	v_mfma_i32_16x16x64_i8 v[50:53], v[180:183], v[188:191], v[50:53]
	v_mfma_i32_16x16x64_i8 v[38:41], v[172:175], v[196:199], v[38:41]
	v_mfma_i32_16x16x64_i8 v[34:37], v[180:183], v[196:199], v[34:37]
	v_mfma_i32_16x16x64_i8 v[22:25], v[172:175], v[204:207], v[22:25]
	v_mfma_i32_16x16x64_i8 v[18:21], v[180:183], v[204:207], v[18:21]
	v_mfma_i32_16x16x64_i8 v[6:9], v[172:175], v[212:215], v[6:9]
	v_mfma_i32_16x16x64_i8 v[2:5], v[180:183], v[212:215], v[2:5]
	s_barrier
	s_setprio 0
	s_add_i32 s13, s13, 2
	s_add_u32 s6, s6, 0x100
	s_addc_u32 s7, s7, 0
	s_add_u32 s8, s8, 0x100
	s_addc_u32 s12, s12, 0
	s_cmpk_gt_u32 s13, 0x53
	s_cbranch_scc0 .LBB0_362
	s_and_b64 vcc, exec, s[46:47]
	s_cbranch_vccz .LBB0_365
	s_barrier

.LBB0_541:
	ds_read_b128 v[146:149], v154
	ds_read_b128 v[158:161], v154 offset:1024
	ds_read_b128 v[162:165], v154 offset:2048
	ds_read_b128 v[166:169], v154 offset:3072
	ds_read_b128 v[170:173], v155
	ds_read_b128 v[174:177], v155 offset:1024
	ds_read_b128 v[178:181], v155 offset:2048
	ds_read_b128 v[182:185], v155 offset:3072
	s_add_u32 s18, s84, 0xfff00080
	s_addc_u32 s19, s85, -1
	s_cmp_eq_u32 s17, 60
	s_cselect_b32 s89, s5, s19
	s_cselect_b32 s88, s8, s18
	s_cselect_b32 s87, s9, s16
	s_cselect_b32 s86, s12, s13
	v_lshl_add_u64 v[218:219], s[84:85], 0, v[138:139]
	s_add_i32 m0, s56, 0xc000
	ds_read_b128 v[186:189], v156
	ds_read_b128 v[190:193], v156 offset:1024
	ds_read_b128 v[194:197], v156 offset:2048
	ds_read_b128 v[198:201], v156 offset:3072
	ds_read_b128 v[202:205], v156 offset:4096
	ds_read_b128 v[206:209], v156 offset:5120
	ds_read_b128 v[210:213], v156 offset:6144
	ds_read_b128 v[214:217], v156 offset:7168
	global_load_lds_dwordx4 v[218:219], off
	v_lshl_add_u64 v[218:219], s[84:85], 0, v[140:141]
	s_add_i32 m0, s56, 0xe000
	s_nop 0
	global_load_lds_dwordx4 v[218:219], off
	s_waitcnt vmcnt(8)
	s_waitcnt lgkmcnt(0)
	s_setprio 1
	s_barrier
	v_mfma_f32_16x16x32_bf16 v[126:129], v[146:149], v[186:189], v[126:129]
	v_mfma_f32_16x16x32_bf16 v[122:125], v[162:165], v[186:189], v[122:125]
	v_mfma_f32_16x16x32_bf16 v[110:113], v[146:149], v[194:197], v[110:113]
	v_mfma_f32_16x16x32_bf16 v[106:109], v[162:165], v[194:197], v[106:109]
	v_mfma_f32_16x16x32_bf16 v[94:97], v[146:149], v[202:205], v[94:97]
	v_mfma_f32_16x16x32_bf16 v[90:93], v[162:165], v[202:205], v[90:93]
	v_mfma_f32_16x16x32_bf16 v[78:81], v[146:149], v[210:213], v[78:81]
	v_mfma_f32_16x16x32_bf16 v[74:77], v[162:165], v[210:213], v[74:77]
	v_mfma_f32_16x16x32_bf16 v[126:129], v[158:161], v[190:193], v[126:129]
	v_mfma_f32_16x16x32_bf16 v[122:125], v[166:169], v[190:193], v[122:125]
	v_mfma_f32_16x16x32_bf16 v[110:113], v[158:161], v[198:201], v[110:113]
	v_mfma_f32_16x16x32_bf16 v[106:109], v[166:169], v[198:201], v[106:109]
	v_mfma_f32_16x16x32_bf16 v[94:97], v[158:161], v[206:209], v[94:97]
	v_mfma_f32_16x16x32_bf16 v[90:93], v[166:169], v[206:209], v[90:93]
	v_mfma_f32_16x16x32_bf16 v[78:81], v[158:161], v[214:217], v[78:81]
	v_mfma_f32_16x16x32_bf16 v[74:77], v[166:169], v[214:217], v[74:77]
	s_setprio 0
	s_setprio 1
	v_mfma_f32_16x16x32_bf16 v[118:121], v[170:173], v[186:189], v[118:121]
	v_mfma_f32_16x16x32_bf16 v[114:117], v[178:181], v[186:189], v[114:117]
	v_mfma_f32_16x16x32_bf16 v[102:105], v[170:173], v[194:197], v[102:105]
	v_mfma_f32_16x16x32_bf16 v[98:101], v[178:181], v[194:197], v[98:101]
	v_mfma_f32_16x16x32_bf16 v[86:89], v[170:173], v[202:205], v[86:89]
	v_mfma_f32_16x16x32_bf16 v[82:85], v[178:181], v[202:205], v[82:85]
	v_mfma_f32_16x16x32_bf16 v[70:73], v[170:173], v[210:213], v[70:73]
	v_mfma_f32_16x16x32_bf16 v[66:69], v[178:181], v[210:213], v[66:69]
	v_mfma_f32_16x16x32_bf16 v[118:121], v[174:177], v[190:193], v[118:121]
	v_mfma_f32_16x16x32_bf16 v[114:117], v[182:185], v[190:193], v[114:117]
	v_mfma_f32_16x16x32_bf16 v[102:105], v[174:177], v[198:201], v[102:105]
	v_mfma_f32_16x16x32_bf16 v[98:101], v[182:185], v[198:201], v[98:101]
	v_mfma_f32_16x16x32_bf16 v[86:89], v[174:177], v[206:209], v[86:89]
	v_mfma_f32_16x16x32_bf16 v[82:85], v[182:185], v[206:209], v[82:85]
	v_mfma_f32_16x16x32_bf16 v[70:73], v[174:177], v[214:217], v[70:73]
	v_mfma_f32_16x16x32_bf16 v[66:69], v[182:185], v[214:217], v[66:69]
	s_barrier
	s_setprio 0
	s_add_i32 s18, s83, s35
	v_lshl_add_u64 v[218:219], s[86:87], 0, v[132:133]
	s_mov_b32 m0, s18
	ds_read_b128 v[186:189], v156 offset:16384
	ds_read_b128 v[190:193], v156 offset:17408
	ds_read_b128 v[194:197], v156 offset:18432
	ds_read_b128 v[198:201], v156 offset:19456
	ds_read_b128 v[202:205], v156 offset:20480
	ds_read_b128 v[206:209], v156 offset:21504
	ds_read_b128 v[210:213], v156 offset:22528
	ds_read_b128 v[214:217], v156 offset:23552
	global_load_lds_dwordx4 v[218:219], off
	s_add_i32 m0, s18, 0x2000
	s_add_u32 s18, s86, 0x100000
	v_lshl_add_u64 v[220:221], s[86:87], 0, v[136:137]
	s_addc_u32 s19, s87, 0
	s_add_i32 s20, s90, s35
	global_load_lds_dwordx4 v[220:221], off
	v_lshl_add_u64 v[222:223], s[18:19], 0, v[132:133]
	s_mov_b32 m0, s20
	v_lshl_add_u64 v[224:225], s[88:89], 0, v[134:135]
	global_load_lds_dwordx4 v[222:223], off
	v_lshl_add_u64 v[222:223], s[18:19], 0, v[136:137]
	s_add_i32 m0, s20, 0x2000
	s_nop 0
	global_load_lds_dwordx4 v[222:223], off
	v_lshl_add_u64 v[222:223], s[88:89], 0, v[130:131]
	s_mov_b32 m0, s56
	s_nop 0
	global_load_lds_dwordx4 v[222:223], off
	s_mov_b32 m0, s57
	s_nop 0
	global_load_lds_dwordx4 v[224:225], off
	s_waitcnt vmcnt(8)
	s_waitcnt lgkmcnt(0)
	s_setprio 1
	s_barrier
	v_mfma_f32_16x16x32_bf16 v[62:65], v[146:149], v[186:189], v[62:65]
	v_mfma_f32_16x16x32_bf16 v[58:61], v[162:165], v[186:189], v[58:61]
	v_mfma_f32_16x16x32_bf16 v[46:49], v[146:149], v[194:197], v[46:49]
	v_mfma_f32_16x16x32_bf16 v[42:45], v[162:165], v[194:197], v[42:45]
	v_mfma_f32_16x16x32_bf16 v[30:33], v[146:149], v[202:205], v[30:33]
	v_mfma_f32_16x16x32_bf16 v[26:29], v[162:165], v[202:205], v[26:29]
	v_mfma_f32_16x16x32_bf16 v[14:17], v[146:149], v[210:213], v[14:17]
	v_mfma_f32_16x16x32_bf16 v[10:13], v[162:165], v[210:213], v[10:13]
	v_mfma_f32_16x16x32_bf16 v[62:65], v[158:161], v[190:193], v[62:65]
	v_mfma_f32_16x16x32_bf16 v[58:61], v[166:169], v[190:193], v[58:61]
	v_mfma_f32_16x16x32_bf16 v[46:49], v[158:161], v[198:201], v[46:49]
	v_mfma_f32_16x16x32_bf16 v[42:45], v[166:169], v[198:201], v[42:45]
	v_mfma_f32_16x16x32_bf16 v[30:33], v[158:161], v[206:209], v[30:33]
	v_mfma_f32_16x16x32_bf16 v[26:29], v[166:169], v[206:209], v[26:29]
	v_mfma_f32_16x16x32_bf16 v[14:17], v[158:161], v[214:217], v[14:17]
	v_mfma_f32_16x16x32_bf16 v[10:13], v[166:169], v[214:217], v[10:13]
	s_setprio 0
	s_setprio 1
	v_mfma_f32_16x16x32_bf16 v[54:57], v[170:173], v[186:189], v[54:57]
	v_mfma_f32_16x16x32_bf16 v[50:53], v[178:181], v[186:189], v[50:53]
	v_mfma_f32_16x16x32_bf16 v[38:41], v[170:173], v[194:197], v[38:41]
	v_mfma_f32_16x16x32_bf16 v[34:37], v[178:181], v[194:197], v[34:37]
	v_mfma_f32_16x16x32_bf16 v[22:25], v[170:173], v[202:205], v[22:25]
	v_mfma_f32_16x16x32_bf16 v[18:21], v[178:181], v[202:205], v[18:21]
	v_mfma_f32_16x16x32_bf16 v[6:9], v[170:173], v[210:213], v[6:9]
	v_mfma_f32_16x16x32_bf16 v[2:5], v[178:181], v[210:213], v[2:5]
	v_mfma_f32_16x16x32_bf16 v[54:57], v[174:177], v[190:193], v[54:57]
	v_mfma_f32_16x16x32_bf16 v[50:53], v[182:185], v[190:193], v[50:53]
	v_mfma_f32_16x16x32_bf16 v[38:41], v[174:177], v[198:201], v[38:41]
	v_mfma_f32_16x16x32_bf16 v[34:37], v[182:185], v[198:201], v[34:37]
	v_mfma_f32_16x16x32_bf16 v[22:25], v[174:177], v[206:209], v[22:25]
	v_mfma_f32_16x16x32_bf16 v[18:21], v[182:185], v[206:209], v[18:21]
	v_mfma_f32_16x16x32_bf16 v[6:9], v[174:177], v[214:217], v[6:9]
	v_mfma_f32_16x16x32_bf16 v[2:5], v[182:185], v[214:217], v[2:5]
	s_barrier
	s_setprio 0
	s_add_i32 s20, 0, 0x18000
	v_add_u32_e32 v150, s20, v151
	s_add_i32 s21, 0, 0x1c000
	ds_read_b128 v[146:149], v150
	ds_read_b128 v[158:161], v150 offset:1024
	ds_read_b128 v[162:165], v150 offset:2048
	ds_read_b128 v[166:169], v150 offset:3072
	v_add_u32_e32 v150, s21, v151
	ds_read_b128 v[170:173], v150
	ds_read_b128 v[174:177], v150 offset:1024
	ds_read_b128 v[178:181], v150 offset:2048
	ds_read_b128 v[182:185], v150 offset:3072
	s_add_u32 s18, s88, 0x100000
	s_addc_u32 s19, s89, 0
	s_mov_b32 m0, s58
	v_lshl_add_u64 v[228:229], s[18:19], 0, v[130:131]
	ds_read_b128 v[186:189], v156 offset:32768
	ds_read_b128 v[190:193], v156 offset:33792
	ds_read_b128 v[194:197], v156 offset:34816
	ds_read_b128 v[198:201], v156 offset:35840
	ds_read_b128 v[202:205], v156 offset:36864
	ds_read_b128 v[206:209], v156 offset:37888
	ds_read_b128 v[210:213], v156 offset:38912
	ds_read_b128 v[214:217], v156 offset:39936
	global_load_lds_dwordx4 v[228:229], off
	v_lshl_add_u64 v[228:229], s[18:19], 0, v[134:135]
	s_mov_b32 m0, s59
	s_nop 0
	global_load_lds_dwordx4 v[228:229], off
	s_waitcnt vmcnt(8)
	s_waitcnt lgkmcnt(0)
	s_setprio 1
	s_barrier
	v_mfma_f32_16x16x32_bf16 v[126:129], v[146:149], v[186:189], v[126:129]
	v_mfma_f32_16x16x32_bf16 v[122:125], v[162:165], v[186:189], v[122:125]
	v_mfma_f32_16x16x32_bf16 v[110:113], v[146:149], v[194:197], v[110:113]
	v_mfma_f32_16x16x32_bf16 v[106:109], v[162:165], v[194:197], v[106:109]
	v_mfma_f32_16x16x32_bf16 v[94:97], v[146:149], v[202:205], v[94:97]
	v_mfma_f32_16x16x32_bf16 v[90:93], v[162:165], v[202:205], v[90:93]
	v_mfma_f32_16x16x32_bf16 v[78:81], v[146:149], v[210:213], v[78:81]
	v_mfma_f32_16x16x32_bf16 v[74:77], v[162:165], v[210:213], v[74:77]
	v_mfma_f32_16x16x32_bf16 v[126:129], v[158:161], v[190:193], v[126:129]
	v_mfma_f32_16x16x32_bf16 v[122:125], v[166:169], v[190:193], v[122:125]
	v_mfma_f32_16x16x32_bf16 v[110:113], v[158:161], v[198:201], v[110:113]
	v_mfma_f32_16x16x32_bf16 v[106:109], v[166:169], v[198:201], v[106:109]
	v_mfma_f32_16x16x32_bf16 v[94:97], v[158:161], v[206:209], v[94:97]
	v_mfma_f32_16x16x32_bf16 v[90:93], v[166:169], v[206:209], v[90:93]
	v_mfma_f32_16x16x32_bf16 v[78:81], v[158:161], v[214:217], v[78:81]
	v_mfma_f32_16x16x32_bf16 v[74:77], v[166:169], v[214:217], v[74:77]
	s_setprio 0
	s_setprio 1
	v_mfma_f32_16x16x32_bf16 v[118:121], v[170:173], v[186:189], v[118:121]
	v_mfma_f32_16x16x32_bf16 v[114:117], v[178:181], v[186:189], v[114:117]
	v_mfma_f32_16x16x32_bf16 v[102:105], v[170:173], v[194:197], v[102:105]
	v_mfma_f32_16x16x32_bf16 v[98:101], v[178:181], v[194:197], v[98:101]
	v_mfma_f32_16x16x32_bf16 v[86:89], v[170:173], v[202:205], v[86:89]
	v_mfma_f32_16x16x32_bf16 v[82:85], v[178:181], v[202:205], v[82:85]
	v_mfma_f32_16x16x32_bf16 v[70:73], v[170:173], v[210:213], v[70:73]
	v_mfma_f32_16x16x32_bf16 v[66:69], v[178:181], v[210:213], v[66:69]
	v_mfma_f32_16x16x32_bf16 v[118:121], v[174:177], v[190:193], v[118:121]
	v_mfma_f32_16x16x32_bf16 v[114:117], v[182:185], v[190:193], v[114:117]
	v_mfma_f32_16x16x32_bf16 v[102:105], v[174:177], v[198:201], v[102:105]
	v_mfma_f32_16x16x32_bf16 v[98:101], v[182:185], v[198:201], v[98:101]
	v_mfma_f32_16x16x32_bf16 v[86:89], v[174:177], v[206:209], v[86:89]
	v_mfma_f32_16x16x32_bf16 v[82:85], v[182:185], v[206:209], v[82:85]
	v_mfma_f32_16x16x32_bf16 v[70:73], v[174:177], v[214:217], v[70:73]
	v_mfma_f32_16x16x32_bf16 v[66:69], v[182:185], v[214:217], v[66:69]
	s_barrier
	s_setprio 0
	s_add_i32 s18, s20, s35
	v_lshl_add_u64 v[218:219], v[218:219], 0, s[40:41]
	s_mov_b32 m0, s18
	ds_read_b128 v[186:189], v156 offset:49152
	ds_read_b128 v[190:193], v156 offset:50176
	ds_read_b128 v[194:197], v156 offset:51200
	ds_read_b128 v[198:201], v156 offset:52224
	ds_read_b128 v[202:205], v156 offset:53248
	ds_read_b128 v[206:209], v156 offset:54272
	ds_read_b128 v[210:213], v156 offset:55296
	ds_read_b128 v[214:217], v156 offset:56320
	global_load_lds_dwordx4 v[218:219], off
	s_add_i32 m0, s18, 0x2000
	s_add_u32 s18, s86, 0x100080
	v_lshl_add_u64 v[218:219], v[220:221], 0, s[40:41]
	s_addc_u32 s19, s87, 0
	s_add_i32 s20, s21, s35
	global_load_lds_dwordx4 v[218:219], off
	v_lshl_add_u64 v[218:219], s[18:19], 0, v[132:133]
	s_mov_b32 m0, s20
	s_nop 0
	global_load_lds_dwordx4 v[218:219], off
	v_lshl_add_u64 v[218:219], s[18:19], 0, v[136:137]
	s_add_i32 m0, s20, 0x2000
	s_nop 0
	global_load_lds_dwordx4 v[218:219], off
	v_lshl_add_u64 v[218:219], v[222:223], 0, s[40:41]
	s_mov_b32 m0, s66
	s_nop 0
	global_load_lds_dwordx4 v[218:219], off
	v_lshl_add_u64 v[218:219], v[224:225], 0, s[40:41]
	s_mov_b32 m0, s67
	s_nop 0
	global_load_lds_dwordx4 v[218:219], off
	s_waitcnt vmcnt(8)
	s_waitcnt lgkmcnt(0)
	s_setprio 1
	s_barrier
	v_mfma_f32_16x16x32_bf16 v[62:65], v[146:149], v[186:189], v[62:65]
	v_mfma_f32_16x16x32_bf16 v[58:61], v[162:165], v[186:189], v[58:61]
	v_mfma_f32_16x16x32_bf16 v[46:49], v[146:149], v[194:197], v[46:49]
	v_mfma_f32_16x16x32_bf16 v[42:45], v[162:165], v[194:197], v[42:45]
	v_mfma_f32_16x16x32_bf16 v[30:33], v[146:149], v[202:205], v[30:33]
	v_mfma_f32_16x16x32_bf16 v[26:29], v[162:165], v[202:205], v[26:29]
	v_mfma_f32_16x16x32_bf16 v[14:17], v[146:149], v[210:213], v[14:17]
	v_mfma_f32_16x16x32_bf16 v[10:13], v[162:165], v[210:213], v[10:13]
	v_mfma_f32_16x16x32_bf16 v[62:65], v[158:161], v[190:193], v[62:65]
	v_mfma_f32_16x16x32_bf16 v[58:61], v[166:169], v[190:193], v[58:61]
	v_mfma_f32_16x16x32_bf16 v[46:49], v[158:161], v[198:201], v[46:49]
	v_mfma_f32_16x16x32_bf16 v[42:45], v[166:169], v[198:201], v[42:45]
	v_mfma_f32_16x16x32_bf16 v[30:33], v[158:161], v[206:209], v[30:33]
	v_mfma_f32_16x16x32_bf16 v[26:29], v[166:169], v[206:209], v[26:29]
	v_mfma_f32_16x16x32_bf16 v[14:17], v[158:161], v[214:217], v[14:17]
	v_mfma_f32_16x16x32_bf16 v[10:13], v[166:169], v[214:217], v[10:13]
	s_setprio 0
	s_setprio 1
	v_mfma_f32_16x16x32_bf16 v[54:57], v[170:173], v[186:189], v[54:57]
	v_mfma_f32_16x16x32_bf16 v[50:53], v[178:181], v[186:189], v[50:53]
	v_mfma_f32_16x16x32_bf16 v[38:41], v[170:173], v[194:197], v[38:41]
	v_mfma_f32_16x16x32_bf16 v[34:37], v[178:181], v[194:197], v[34:37]
	v_mfma_f32_16x16x32_bf16 v[22:25], v[170:173], v[202:205], v[22:25]
	v_mfma_f32_16x16x32_bf16 v[18:21], v[178:181], v[202:205], v[18:21]
	v_mfma_f32_16x16x32_bf16 v[6:9], v[170:173], v[210:213], v[6:9]
	v_mfma_f32_16x16x32_bf16 v[2:5], v[178:181], v[210:213], v[2:5]
	v_mfma_f32_16x16x32_bf16 v[54:57], v[174:177], v[190:193], v[54:57]
	v_mfma_f32_16x16x32_bf16 v[50:53], v[182:185], v[190:193], v[50:53]
	v_mfma_f32_16x16x32_bf16 v[38:41], v[174:177], v[198:201], v[38:41]
	v_mfma_f32_16x16x32_bf16 v[34:37], v[182:185], v[198:201], v[34:37]
	v_mfma_f32_16x16x32_bf16 v[22:25], v[174:177], v[206:209], v[22:25]
	v_mfma_f32_16x16x32_bf16 v[18:21], v[182:185], v[206:209], v[18:21]
	v_mfma_f32_16x16x32_bf16 v[6:9], v[174:177], v[214:217], v[6:9]
	v_mfma_f32_16x16x32_bf16 v[2:5], v[182:185], v[214:217], v[2:5]
	s_barrier
	s_setprio 0
	s_add_i32 s17, s17, 2
	s_add_u32 s84, s84, 0x100
	s_addc_u32 s85, s85, 0
	s_add_u32 s13, s13, 0x100
	s_addc_u32 s16, s16, 0
	s_cmp_gt_u32 s17, 61
	s_cbranch_scc0 .LBB0_541
	s_and_b64 vcc, exec, s[42:43]
	s_cbranch_vccz .LBB0_544
	s_barrier

.LBB0_886:
	ds_read_b128 v[154:157], v150
	ds_read_b128 v[158:161], v150 offset:1024
	ds_read_b128 v[162:165], v150 offset:2048
	ds_read_b128 v[166:169], v150 offset:3072
	ds_read_b128 v[170:173], v151
	ds_read_b128 v[174:177], v151 offset:1024
	ds_read_b128 v[178:181], v151 offset:2048
	ds_read_b128 v[182:185], v151 offset:3072
	s_add_u32 s50, s48, 0xfff00080
	s_addc_u32 s51, s49, -1
	s_cmp_eq_u32 s78, 60
	s_cselect_b32 s53, s8, s51
	s_cselect_b32 s52, s9, s50
	s_cselect_b32 s51, s12, s41
	s_cselect_b32 s50, s13, s29
	v_lshl_add_u64 v[146:147], s[48:49], 0, v[138:139]
	s_add_i32 m0, s47, 0xc000
	ds_read_b128 v[186:189], v152
	ds_read_b128 v[190:193], v152 offset:1024
	ds_read_b128 v[194:197], v152 offset:2048
	ds_read_b128 v[198:201], v152 offset:3072
	ds_read_b128 v[202:205], v152 offset:4096
	ds_read_b128 v[206:209], v152 offset:5120
	ds_read_b128 v[210:213], v152 offset:6144
	ds_read_b128 v[214:217], v152 offset:7168
	global_load_lds_dwordx4 v[146:147], off
	v_lshl_add_u64 v[146:147], s[48:49], 0, v[140:141]
	s_add_i32 m0, s47, 0xe000
	s_nop 0
	global_load_lds_dwordx4 v[146:147], off
	s_waitcnt vmcnt(8)
	s_waitcnt lgkmcnt(0)
	s_setprio 1
	s_barrier
	v_mfma_f32_16x16x32_bf16 v[126:129], v[154:157], v[186:189], v[126:129]
	v_mfma_f32_16x16x32_bf16 v[122:125], v[162:165], v[186:189], v[122:125]
	v_mfma_f32_16x16x32_bf16 v[118:121], v[154:157], v[194:197], v[118:121]
	v_mfma_f32_16x16x32_bf16 v[110:113], v[162:165], v[194:197], v[110:113]
	v_mfma_f32_16x16x32_bf16 v[102:105], v[154:157], v[202:205], v[102:105]
	v_mfma_f32_16x16x32_bf16 v[94:97], v[162:165], v[202:205], v[94:97]
	v_mfma_f32_16x16x32_bf16 v[86:89], v[154:157], v[210:213], v[86:89]
	v_mfma_f32_16x16x32_bf16 v[78:81], v[162:165], v[210:213], v[78:81]
	v_mfma_f32_16x16x32_bf16 v[126:129], v[158:161], v[190:193], v[126:129]
	v_mfma_f32_16x16x32_bf16 v[122:125], v[166:169], v[190:193], v[122:125]
	v_mfma_f32_16x16x32_bf16 v[118:121], v[158:161], v[198:201], v[118:121]
	v_mfma_f32_16x16x32_bf16 v[110:113], v[166:169], v[198:201], v[110:113]
	v_mfma_f32_16x16x32_bf16 v[102:105], v[158:161], v[206:209], v[102:105]
	v_mfma_f32_16x16x32_bf16 v[94:97], v[166:169], v[206:209], v[94:97]
	v_mfma_f32_16x16x32_bf16 v[86:89], v[158:161], v[214:217], v[86:89]
	v_mfma_f32_16x16x32_bf16 v[78:81], v[166:169], v[214:217], v[78:81]
	s_setprio 0
	s_setprio 1
	v_mfma_f32_16x16x32_bf16 v[114:117], v[170:173], v[186:189], v[114:117]
	v_mfma_f32_16x16x32_bf16 v[106:109], v[178:181], v[186:189], v[106:109]
	v_mfma_f32_16x16x32_bf16 v[98:101], v[170:173], v[194:197], v[98:101]
	v_mfma_f32_16x16x32_bf16 v[90:93], v[178:181], v[194:197], v[90:93]
	v_mfma_f32_16x16x32_bf16 v[82:85], v[170:173], v[202:205], v[82:85]
	v_mfma_f32_16x16x32_bf16 v[74:77], v[178:181], v[202:205], v[74:77]
	v_mfma_f32_16x16x32_bf16 v[70:73], v[170:173], v[210:213], v[70:73]
	v_mfma_f32_16x16x32_bf16 v[66:69], v[178:181], v[210:213], v[66:69]
	v_mfma_f32_16x16x32_bf16 v[114:117], v[174:177], v[190:193], v[114:117]
	v_mfma_f32_16x16x32_bf16 v[106:109], v[182:185], v[190:193], v[106:109]
	v_mfma_f32_16x16x32_bf16 v[98:101], v[174:177], v[198:201], v[98:101]
	v_mfma_f32_16x16x32_bf16 v[90:93], v[182:185], v[198:201], v[90:93]
	v_mfma_f32_16x16x32_bf16 v[82:85], v[174:177], v[206:209], v[82:85]
	v_mfma_f32_16x16x32_bf16 v[74:77], v[182:185], v[206:209], v[74:77]
	v_mfma_f32_16x16x32_bf16 v[70:73], v[174:177], v[214:217], v[70:73]
	v_mfma_f32_16x16x32_bf16 v[66:69], v[182:185], v[214:217], v[66:69]
	s_barrier
	s_setprio 0
	s_add_i32 s79, s67, s54
	v_lshl_add_u64 v[146:147], s[50:51], 0, v[132:133]
	s_mov_b32 m0, s79
	ds_read_b128 v[186:189], v152 offset:16384
	ds_read_b128 v[190:193], v152 offset:17408
	ds_read_b128 v[194:197], v152 offset:18432
	ds_read_b128 v[198:201], v152 offset:19456
	ds_read_b128 v[202:205], v152 offset:20480
	ds_read_b128 v[206:209], v152 offset:21504
	ds_read_b128 v[210:213], v152 offset:22528
	ds_read_b128 v[214:217], v152 offset:23552
	global_load_lds_dwordx4 v[146:147], off
	s_add_i32 m0, s79, 0x2000
	s_add_u32 s80, s50, 0x100000
	v_lshl_add_u64 v[218:219], s[50:51], 0, v[136:137]
	s_addc_u32 s81, s51, 0
	s_add_i32 s79, s68, s54
	global_load_lds_dwordx4 v[218:219], off
	v_lshl_add_u64 v[220:221], s[80:81], 0, v[132:133]
	s_mov_b32 m0, s79
	v_lshl_add_u64 v[222:223], s[52:53], 0, v[134:135]
	global_load_lds_dwordx4 v[220:221], off
	v_lshl_add_u64 v[220:221], s[80:81], 0, v[136:137]
	s_add_i32 m0, s79, 0x2000
	s_nop 0
	global_load_lds_dwordx4 v[220:221], off
	v_lshl_add_u64 v[220:221], s[52:53], 0, v[130:131]
	s_mov_b32 m0, s47
	s_nop 0
	global_load_lds_dwordx4 v[220:221], off
	s_mov_b32 m0, s55
	s_nop 0
	global_load_lds_dwordx4 v[222:223], off
	s_waitcnt vmcnt(8)
	s_waitcnt lgkmcnt(0)
	s_setprio 1
	s_barrier
	v_mfma_f32_16x16x32_bf16 v[62:65], v[154:157], v[186:189], v[62:65]
	v_mfma_f32_16x16x32_bf16 v[58:61], v[162:165], v[186:189], v[58:61]
	v_mfma_f32_16x16x32_bf16 v[54:57], v[154:157], v[194:197], v[54:57]
	v_mfma_f32_16x16x32_bf16 v[46:49], v[162:165], v[194:197], v[46:49]
	v_mfma_f32_16x16x32_bf16 v[38:41], v[154:157], v[202:205], v[38:41]
	v_mfma_f32_16x16x32_bf16 v[30:33], v[162:165], v[202:205], v[30:33]
	v_mfma_f32_16x16x32_bf16 v[22:25], v[154:157], v[210:213], v[22:25]
	v_mfma_f32_16x16x32_bf16 v[14:17], v[162:165], v[210:213], v[14:17]
	v_mfma_f32_16x16x32_bf16 v[62:65], v[158:161], v[190:193], v[62:65]
	v_mfma_f32_16x16x32_bf16 v[58:61], v[166:169], v[190:193], v[58:61]
	v_mfma_f32_16x16x32_bf16 v[54:57], v[158:161], v[198:201], v[54:57]
	v_mfma_f32_16x16x32_bf16 v[46:49], v[166:169], v[198:201], v[46:49]
	v_mfma_f32_16x16x32_bf16 v[38:41], v[158:161], v[206:209], v[38:41]
	v_mfma_f32_16x16x32_bf16 v[30:33], v[166:169], v[206:209], v[30:33]
	v_mfma_f32_16x16x32_bf16 v[22:25], v[158:161], v[214:217], v[22:25]
	v_mfma_f32_16x16x32_bf16 v[14:17], v[166:169], v[214:217], v[14:17]
	s_setprio 0
	s_setprio 1
	v_mfma_f32_16x16x32_bf16 v[50:53], v[170:173], v[186:189], v[50:53]
	v_mfma_f32_16x16x32_bf16 v[42:45], v[178:181], v[186:189], v[42:45]
	v_mfma_f32_16x16x32_bf16 v[34:37], v[170:173], v[194:197], v[34:37]
	v_mfma_f32_16x16x32_bf16 v[26:29], v[178:181], v[194:197], v[26:29]
	v_mfma_f32_16x16x32_bf16 v[18:21], v[170:173], v[202:205], v[18:21]
	v_mfma_f32_16x16x32_bf16 v[10:13], v[178:181], v[202:205], v[10:13]
	v_mfma_f32_16x16x32_bf16 v[6:9], v[170:173], v[210:213], v[6:9]
	v_mfma_f32_16x16x32_bf16 v[2:5], v[178:181], v[210:213], v[2:5]
	v_mfma_f32_16x16x32_bf16 v[50:53], v[174:177], v[190:193], v[50:53]
	v_mfma_f32_16x16x32_bf16 v[42:45], v[182:185], v[190:193], v[42:45]
	v_mfma_f32_16x16x32_bf16 v[34:37], v[174:177], v[198:201], v[34:37]
	v_mfma_f32_16x16x32_bf16 v[26:29], v[182:185], v[198:201], v[26:29]
	v_mfma_f32_16x16x32_bf16 v[18:21], v[174:177], v[206:209], v[18:21]
	v_mfma_f32_16x16x32_bf16 v[10:13], v[182:185], v[206:209], v[10:13]
	v_mfma_f32_16x16x32_bf16 v[6:9], v[174:177], v[214:217], v[6:9]
	v_mfma_f32_16x16x32_bf16 v[2:5], v[182:185], v[214:217], v[2:5]
	s_barrier
	s_setprio 0
	s_add_i32 s79, 0, 0x18000
	v_add_u32_e32 v153, s79, v148
	s_add_i32 s80, 0, 0x1c000
	ds_read_b128 v[154:157], v153
	ds_read_b128 v[158:161], v153 offset:1024
	ds_read_b128 v[162:165], v153 offset:2048
	ds_read_b128 v[166:169], v153 offset:3072
	v_add_u32_e32 v153, s80, v148
	ds_read_b128 v[170:173], v153
	ds_read_b128 v[174:177], v153 offset:1024
	ds_read_b128 v[178:181], v153 offset:2048
	ds_read_b128 v[182:185], v153 offset:3072
	s_add_u32 s52, s52, 0x100000
	s_addc_u32 s53, s53, 0
	s_mov_b32 m0, s56
	v_lshl_add_u64 v[224:225], s[52:53], 0, v[130:131]
	ds_read_b128 v[186:189], v152 offset:32768
	ds_read_b128 v[190:193], v152 offset:33792
	ds_read_b128 v[194:197], v152 offset:34816
	ds_read_b128 v[198:201], v152 offset:35840
	ds_read_b128 v[202:205], v152 offset:36864
	ds_read_b128 v[206:209], v152 offset:37888
	ds_read_b128 v[210:213], v152 offset:38912
	ds_read_b128 v[214:217], v152 offset:39936
	global_load_lds_dwordx4 v[224:225], off
	v_lshl_add_u64 v[224:225], s[52:53], 0, v[134:135]
	s_mov_b32 m0, s57
	s_nop 0
	global_load_lds_dwordx4 v[224:225], off
	s_waitcnt vmcnt(8)
	s_waitcnt lgkmcnt(0)
	s_setprio 1
	s_barrier
	v_mfma_f32_16x16x32_bf16 v[126:129], v[154:157], v[186:189], v[126:129]
	v_mfma_f32_16x16x32_bf16 v[122:125], v[162:165], v[186:189], v[122:125]
	v_mfma_f32_16x16x32_bf16 v[118:121], v[154:157], v[194:197], v[118:121]
	v_mfma_f32_16x16x32_bf16 v[110:113], v[162:165], v[194:197], v[110:113]
	v_mfma_f32_16x16x32_bf16 v[102:105], v[154:157], v[202:205], v[102:105]
	v_mfma_f32_16x16x32_bf16 v[94:97], v[162:165], v[202:205], v[94:97]
	v_mfma_f32_16x16x32_bf16 v[86:89], v[154:157], v[210:213], v[86:89]
	v_mfma_f32_16x16x32_bf16 v[78:81], v[162:165], v[210:213], v[78:81]
	v_mfma_f32_16x16x32_bf16 v[126:129], v[158:161], v[190:193], v[126:129]
	v_mfma_f32_16x16x32_bf16 v[122:125], v[166:169], v[190:193], v[122:125]
	v_mfma_f32_16x16x32_bf16 v[118:121], v[158:161], v[198:201], v[118:121]
	v_mfma_f32_16x16x32_bf16 v[110:113], v[166:169], v[198:201], v[110:113]
	v_mfma_f32_16x16x32_bf16 v[102:105], v[158:161], v[206:209], v[102:105]
	v_mfma_f32_16x16x32_bf16 v[94:97], v[166:169], v[206:209], v[94:97]
	v_mfma_f32_16x16x32_bf16 v[86:89], v[158:161], v[214:217], v[86:89]
	v_mfma_f32_16x16x32_bf16 v[78:81], v[166:169], v[214:217], v[78:81]
	s_setprio 0
	s_setprio 1
	v_mfma_f32_16x16x32_bf16 v[114:117], v[170:173], v[186:189], v[114:117]
	v_mfma_f32_16x16x32_bf16 v[106:109], v[178:181], v[186:189], v[106:109]
	v_mfma_f32_16x16x32_bf16 v[98:101], v[170:173], v[194:197], v[98:101]
	v_mfma_f32_16x16x32_bf16 v[90:93], v[178:181], v[194:197], v[90:93]
	v_mfma_f32_16x16x32_bf16 v[82:85], v[170:173], v[202:205], v[82:85]
	v_mfma_f32_16x16x32_bf16 v[74:77], v[178:181], v[202:205], v[74:77]
	v_mfma_f32_16x16x32_bf16 v[70:73], v[170:173], v[210:213], v[70:73]
	v_mfma_f32_16x16x32_bf16 v[66:69], v[178:181], v[210:213], v[66:69]
	v_mfma_f32_16x16x32_bf16 v[114:117], v[174:177], v[190:193], v[114:117]
	v_mfma_f32_16x16x32_bf16 v[106:109], v[182:185], v[190:193], v[106:109]
	v_mfma_f32_16x16x32_bf16 v[98:101], v[174:177], v[198:201], v[98:101]
	v_mfma_f32_16x16x32_bf16 v[90:93], v[182:185], v[198:201], v[90:93]
	v_mfma_f32_16x16x32_bf16 v[82:85], v[174:177], v[206:209], v[82:85]
	v_mfma_f32_16x16x32_bf16 v[74:77], v[182:185], v[206:209], v[74:77]
	v_mfma_f32_16x16x32_bf16 v[70:73], v[174:177], v[214:217], v[70:73]
	v_mfma_f32_16x16x32_bf16 v[66:69], v[182:185], v[214:217], v[66:69]
	s_barrier
	s_setprio 0
	s_add_i32 s52, s79, s54
	v_lshl_add_u64 v[146:147], v[146:147], 0, s[16:17]
	s_mov_b32 m0, s52
	ds_read_b128 v[186:189], v152 offset:49152
	ds_read_b128 v[190:193], v152 offset:50176
	ds_read_b128 v[194:197], v152 offset:51200
	ds_read_b128 v[198:201], v152 offset:52224
	ds_read_b128 v[202:205], v152 offset:53248
	ds_read_b128 v[206:209], v152 offset:54272
	ds_read_b128 v[210:213], v152 offset:55296
	ds_read_b128 v[214:217], v152 offset:56320
	global_load_lds_dwordx4 v[146:147], off
	s_add_i32 m0, s52, 0x2000
	s_add_u32 s50, s50, 0x100080
	v_lshl_add_u64 v[146:147], v[218:219], 0, s[16:17]
	s_addc_u32 s51, s51, 0
	s_add_i32 s52, s80, s54
	global_load_lds_dwordx4 v[146:147], off
	v_lshl_add_u64 v[146:147], s[50:51], 0, v[132:133]
	s_mov_b32 m0, s52
	s_nop 0
	global_load_lds_dwordx4 v[146:147], off
	v_lshl_add_u64 v[146:147], s[50:51], 0, v[136:137]
	s_add_i32 m0, s52, 0x2000
	s_nop 0
	global_load_lds_dwordx4 v[146:147], off
	v_lshl_add_u64 v[146:147], v[220:221], 0, s[16:17]
	s_mov_b32 m0, s59
	s_nop 0
	global_load_lds_dwordx4 v[146:147], off
	v_lshl_add_u64 v[146:147], v[222:223], 0, s[16:17]
	s_mov_b32 m0, s61
	s_nop 0
	global_load_lds_dwordx4 v[146:147], off
	s_waitcnt vmcnt(8)
	s_waitcnt lgkmcnt(0)
	s_setprio 1
	s_barrier
	v_mfma_f32_16x16x32_bf16 v[62:65], v[154:157], v[186:189], v[62:65]
	v_mfma_f32_16x16x32_bf16 v[58:61], v[162:165], v[186:189], v[58:61]
	v_mfma_f32_16x16x32_bf16 v[54:57], v[154:157], v[194:197], v[54:57]
	v_mfma_f32_16x16x32_bf16 v[46:49], v[162:165], v[194:197], v[46:49]
	v_mfma_f32_16x16x32_bf16 v[38:41], v[154:157], v[202:205], v[38:41]
	v_mfma_f32_16x16x32_bf16 v[30:33], v[162:165], v[202:205], v[30:33]
	v_mfma_f32_16x16x32_bf16 v[22:25], v[154:157], v[210:213], v[22:25]
	v_mfma_f32_16x16x32_bf16 v[14:17], v[162:165], v[210:213], v[14:17]
	v_mfma_f32_16x16x32_bf16 v[62:65], v[158:161], v[190:193], v[62:65]
	v_mfma_f32_16x16x32_bf16 v[58:61], v[166:169], v[190:193], v[58:61]
	v_mfma_f32_16x16x32_bf16 v[54:57], v[158:161], v[198:201], v[54:57]
	v_mfma_f32_16x16x32_bf16 v[46:49], v[166:169], v[198:201], v[46:49]
	v_mfma_f32_16x16x32_bf16 v[38:41], v[158:161], v[206:209], v[38:41]
	v_mfma_f32_16x16x32_bf16 v[30:33], v[166:169], v[206:209], v[30:33]
	v_mfma_f32_16x16x32_bf16 v[22:25], v[158:161], v[214:217], v[22:25]
	v_mfma_f32_16x16x32_bf16 v[14:17], v[166:169], v[214:217], v[14:17]
	s_setprio 0
	s_setprio 1
	v_mfma_f32_16x16x32_bf16 v[50:53], v[170:173], v[186:189], v[50:53]
	v_mfma_f32_16x16x32_bf16 v[42:45], v[178:181], v[186:189], v[42:45]
	v_mfma_f32_16x16x32_bf16 v[34:37], v[170:173], v[194:197], v[34:37]
	v_mfma_f32_16x16x32_bf16 v[26:29], v[178:181], v[194:197], v[26:29]
	v_mfma_f32_16x16x32_bf16 v[18:21], v[170:173], v[202:205], v[18:21]
	v_mfma_f32_16x16x32_bf16 v[10:13], v[178:181], v[202:205], v[10:13]
	v_mfma_f32_16x16x32_bf16 v[6:9], v[170:173], v[210:213], v[6:9]
	v_mfma_f32_16x16x32_bf16 v[2:5], v[178:181], v[210:213], v[2:5]
	v_mfma_f32_16x16x32_bf16 v[50:53], v[174:177], v[190:193], v[50:53]
	v_mfma_f32_16x16x32_bf16 v[42:45], v[182:185], v[190:193], v[42:45]
	v_mfma_f32_16x16x32_bf16 v[34:37], v[174:177], v[198:201], v[34:37]
	v_mfma_f32_16x16x32_bf16 v[26:29], v[182:185], v[198:201], v[26:29]
	v_mfma_f32_16x16x32_bf16 v[18:21], v[174:177], v[206:209], v[18:21]
	v_mfma_f32_16x16x32_bf16 v[10:13], v[182:185], v[206:209], v[10:13]
	v_mfma_f32_16x16x32_bf16 v[6:9], v[174:177], v[214:217], v[6:9]
	v_mfma_f32_16x16x32_bf16 v[2:5], v[182:185], v[214:217], v[2:5]
	s_barrier
	s_setprio 0
	s_add_i32 s78, s78, 2
	s_add_u32 s48, s48, 0x100
	s_addc_u32 s49, s49, 0
	s_add_u32 s29, s29, 0x100
	s_addc_u32 s41, s41, 0
	s_cmp_gt_u32 s78, 61
	s_cbranch_scc0 .LBB0_886
	s_and_b64 vcc, exec, s[18:19]
	s_cbranch_vccz .LBB0_889
	s_barrier

.LBB0_1015:
	ds_read_b128 v[146:149], v156
	ds_read_b128 v[150:153], v156 offset:1024
	ds_read_b128 v[160:163], v156 offset:2048
	ds_read_b128 v[164:167], v156 offset:3072
	ds_read_b128 v[168:171], v157
	ds_read_b128 v[172:175], v157 offset:1024
	ds_read_b128 v[176:179], v157 offset:2048
	ds_read_b128 v[180:183], v157 offset:3072
	s_add_u32 s44, s42, 0xfff80080
	s_addc_u32 s45, s43, -1
	s_cmp_eq_u32 s67, 28
	s_cselect_b32 s47, s8, s45
	s_cselect_b32 s46, s9, s44
	s_cselect_b32 s45, s21, s66
	s_cselect_b32 s44, s23, s61
	v_lshl_add_u64 v[216:217], s[42:43], 0, v[138:139]
	s_add_i32 m0, s41, 0xc000
	ds_read_b128 v[184:187], v158
	ds_read_b128 v[188:191], v158 offset:1024
	ds_read_b128 v[192:195], v158 offset:2048
	ds_read_b128 v[196:199], v158 offset:3072
	ds_read_b128 v[200:203], v158 offset:4096
	ds_read_b128 v[204:207], v158 offset:5120
	ds_read_b128 v[208:211], v158 offset:6144
	ds_read_b128 v[212:215], v158 offset:7168
	global_load_lds_dwordx4 v[216:217], off
	v_lshl_add_u64 v[216:217], s[42:43], 0, v[140:141]
	s_add_i32 m0, s41, 0xe000
	s_nop 0
	global_load_lds_dwordx4 v[216:217], off
	s_waitcnt vmcnt(8)
	s_waitcnt lgkmcnt(0)
	s_setprio 1
	s_barrier
	v_mfma_i32_16x16x64_i8 v[126:129], v[146:149], v[184:187], v[126:129]
	v_mfma_i32_16x16x64_i8 v[122:125], v[160:163], v[184:187], v[122:125]
	v_mfma_i32_16x16x64_i8 v[110:113], v[146:149], v[192:195], v[110:113]
	v_mfma_i32_16x16x64_i8 v[106:109], v[160:163], v[192:195], v[106:109]
	v_mfma_i32_16x16x64_i8 v[94:97], v[146:149], v[200:203], v[94:97]
	v_mfma_i32_16x16x64_i8 v[90:93], v[160:163], v[200:203], v[90:93]
	v_mfma_i32_16x16x64_i8 v[78:81], v[146:149], v[208:211], v[78:81]
	v_mfma_i32_16x16x64_i8 v[74:77], v[160:163], v[208:211], v[74:77]
	v_mfma_i32_16x16x64_i8 v[126:129], v[150:153], v[188:191], v[126:129]
	v_mfma_i32_16x16x64_i8 v[122:125], v[164:167], v[188:191], v[122:125]
	v_mfma_i32_16x16x64_i8 v[110:113], v[150:153], v[196:199], v[110:113]
	v_mfma_i32_16x16x64_i8 v[106:109], v[164:167], v[196:199], v[106:109]
	v_mfma_i32_16x16x64_i8 v[94:97], v[150:153], v[204:207], v[94:97]
	v_mfma_i32_16x16x64_i8 v[90:93], v[164:167], v[204:207], v[90:93]
	v_mfma_i32_16x16x64_i8 v[78:81], v[150:153], v[212:215], v[78:81]
	v_mfma_i32_16x16x64_i8 v[74:77], v[164:167], v[212:215], v[74:77]
	s_setprio 0
	s_setprio 1
	v_mfma_i32_16x16x64_i8 v[118:121], v[168:171], v[184:187], v[118:121]
	v_mfma_i32_16x16x64_i8 v[114:117], v[176:179], v[184:187], v[114:117]
	v_mfma_i32_16x16x64_i8 v[102:105], v[168:171], v[192:195], v[102:105]
	v_mfma_i32_16x16x64_i8 v[98:101], v[176:179], v[192:195], v[98:101]
	v_mfma_i32_16x16x64_i8 v[86:89], v[168:171], v[200:203], v[86:89]
	v_mfma_i32_16x16x64_i8 v[82:85], v[176:179], v[200:203], v[82:85]
	v_mfma_i32_16x16x64_i8 v[70:73], v[168:171], v[208:211], v[70:73]
	v_mfma_i32_16x16x64_i8 v[66:69], v[176:179], v[208:211], v[66:69]
	v_mfma_i32_16x16x64_i8 v[118:121], v[172:175], v[188:191], v[118:121]
	v_mfma_i32_16x16x64_i8 v[114:117], v[180:183], v[188:191], v[114:117]
	v_mfma_i32_16x16x64_i8 v[102:105], v[172:175], v[196:199], v[102:105]
	v_mfma_i32_16x16x64_i8 v[98:101], v[180:183], v[196:199], v[98:101]
	v_mfma_i32_16x16x64_i8 v[86:89], v[172:175], v[204:207], v[86:89]
	v_mfma_i32_16x16x64_i8 v[82:85], v[180:183], v[204:207], v[82:85]
	v_mfma_i32_16x16x64_i8 v[70:73], v[172:175], v[212:215], v[70:73]
	v_mfma_i32_16x16x64_i8 v[66:69], v[180:183], v[212:215], v[66:69]
	s_barrier
	s_setprio 0
	s_add_i32 s68, s56, s19
	v_lshl_add_u64 v[216:217], s[44:45], 0, v[134:135]
	s_mov_b32 m0, s68
	ds_read_b128 v[184:187], v158 offset:16384
	ds_read_b128 v[188:191], v158 offset:17408
	ds_read_b128 v[192:195], v158 offset:18432
	ds_read_b128 v[196:199], v158 offset:19456
	ds_read_b128 v[200:203], v158 offset:20480
	ds_read_b128 v[204:207], v158 offset:21504
	ds_read_b128 v[208:211], v158 offset:22528
	ds_read_b128 v[212:215], v158 offset:23552
	global_load_lds_dwordx4 v[216:217], off
	s_add_i32 m0, s68, 0x2000
	s_add_u32 s68, s44, 0x80000
	v_lshl_add_u64 v[218:219], s[44:45], 0, v[130:131]
	s_addc_u32 s69, s45, 0
	s_add_i32 s72, s57, s19
	global_load_lds_dwordx4 v[218:219], off
	v_lshl_add_u64 v[220:221], s[68:69], 0, v[134:135]
	s_mov_b32 m0, s72
	v_lshl_add_u64 v[222:223], s[46:47], 0, v[132:133]
	global_load_lds_dwordx4 v[220:221], off
	v_lshl_add_u64 v[220:221], s[68:69], 0, v[130:131]
	s_add_i32 m0, s72, 0x2000
	s_nop 0
	global_load_lds_dwordx4 v[220:221], off
	v_lshl_add_u64 v[220:221], s[46:47], 0, v[136:137]
	s_mov_b32 m0, s41
	s_nop 0
	global_load_lds_dwordx4 v[220:221], off
	s_mov_b32 m0, s49
	s_nop 0
	global_load_lds_dwordx4 v[222:223], off
	s_waitcnt vmcnt(8)
	s_waitcnt lgkmcnt(0)
	s_setprio 1
	s_barrier
	v_mfma_i32_16x16x64_i8 v[62:65], v[146:149], v[184:187], v[62:65]
	v_mfma_i32_16x16x64_i8 v[58:61], v[160:163], v[184:187], v[58:61]
	v_mfma_i32_16x16x64_i8 v[46:49], v[146:149], v[192:195], v[46:49]
	v_mfma_i32_16x16x64_i8 v[42:45], v[160:163], v[192:195], v[42:45]
	v_mfma_i32_16x16x64_i8 v[30:33], v[146:149], v[200:203], v[30:33]
	v_mfma_i32_16x16x64_i8 v[26:29], v[160:163], v[200:203], v[26:29]
	v_mfma_i32_16x16x64_i8 v[14:17], v[146:149], v[208:211], v[14:17]
	v_mfma_i32_16x16x64_i8 v[10:13], v[160:163], v[208:211], v[10:13]
	v_mfma_i32_16x16x64_i8 v[62:65], v[150:153], v[188:191], v[62:65]
	v_mfma_i32_16x16x64_i8 v[58:61], v[164:167], v[188:191], v[58:61]
	v_mfma_i32_16x16x64_i8 v[46:49], v[150:153], v[196:199], v[46:49]
	v_mfma_i32_16x16x64_i8 v[42:45], v[164:167], v[196:199], v[42:45]
	v_mfma_i32_16x16x64_i8 v[30:33], v[150:153], v[204:207], v[30:33]
	v_mfma_i32_16x16x64_i8 v[26:29], v[164:167], v[204:207], v[26:29]
	v_mfma_i32_16x16x64_i8 v[14:17], v[150:153], v[212:215], v[14:17]
	v_mfma_i32_16x16x64_i8 v[10:13], v[164:167], v[212:215], v[10:13]
	s_setprio 0
	s_setprio 1
	v_mfma_i32_16x16x64_i8 v[54:57], v[168:171], v[184:187], v[54:57]
	v_mfma_i32_16x16x64_i8 v[50:53], v[176:179], v[184:187], v[50:53]
	v_mfma_i32_16x16x64_i8 v[38:41], v[168:171], v[192:195], v[38:41]
	v_mfma_i32_16x16x64_i8 v[34:37], v[176:179], v[192:195], v[34:37]
	v_mfma_i32_16x16x64_i8 v[22:25], v[168:171], v[200:203], v[22:25]
	v_mfma_i32_16x16x64_i8 v[18:21], v[176:179], v[200:203], v[18:21]
	v_mfma_i32_16x16x64_i8 v[6:9], v[168:171], v[208:211], v[6:9]
	v_mfma_i32_16x16x64_i8 v[2:5], v[176:179], v[208:211], v[2:5]
	v_mfma_i32_16x16x64_i8 v[54:57], v[172:175], v[188:191], v[54:57]
	v_mfma_i32_16x16x64_i8 v[50:53], v[180:183], v[188:191], v[50:53]
	v_mfma_i32_16x16x64_i8 v[38:41], v[172:175], v[196:199], v[38:41]
	v_mfma_i32_16x16x64_i8 v[34:37], v[180:183], v[196:199], v[34:37]
	v_mfma_i32_16x16x64_i8 v[22:25], v[172:175], v[204:207], v[22:25]
	v_mfma_i32_16x16x64_i8 v[18:21], v[180:183], v[204:207], v[18:21]
	v_mfma_i32_16x16x64_i8 v[6:9], v[172:175], v[212:215], v[6:9]
	v_mfma_i32_16x16x64_i8 v[2:5], v[180:183], v[212:215], v[2:5]
	s_barrier
	s_setprio 0
	s_add_i32 s68, 0, 0x18000
	v_add_u32_e32 v159, s68, v154
	s_add_i32 s69, 0, 0x1c000
	ds_read_b128 v[146:149], v159
	ds_read_b128 v[150:153], v159 offset:1024
	ds_read_b128 v[160:163], v159 offset:2048
	ds_read_b128 v[164:167], v159 offset:3072
	v_add_u32_e32 v159, s69, v154
	ds_read_b128 v[168:171], v159
	ds_read_b128 v[172:175], v159 offset:1024
	ds_read_b128 v[176:179], v159 offset:2048
	ds_read_b128 v[180:183], v159 offset:3072
	s_add_u32 s46, s46, 0x80000
	s_addc_u32 s47, s47, 0
	s_mov_b32 m0, s50
	v_lshl_add_u64 v[224:225], s[46:47], 0, v[136:137]
	ds_read_b128 v[184:187], v158 offset:32768
	ds_read_b128 v[188:191], v158 offset:33792
	ds_read_b128 v[192:195], v158 offset:34816
	ds_read_b128 v[196:199], v158 offset:35840
	ds_read_b128 v[200:203], v158 offset:36864
	ds_read_b128 v[204:207], v158 offset:37888
	ds_read_b128 v[208:211], v158 offset:38912
	ds_read_b128 v[212:215], v158 offset:39936
	global_load_lds_dwordx4 v[224:225], off
	v_lshl_add_u64 v[224:225], s[46:47], 0, v[132:133]
	s_mov_b32 m0, s51
	s_nop 0
	global_load_lds_dwordx4 v[224:225], off
	s_waitcnt vmcnt(8)
	s_waitcnt lgkmcnt(0)
	s_setprio 1
	s_barrier
	v_mfma_i32_16x16x64_i8 v[126:129], v[146:149], v[184:187], v[126:129]
	v_mfma_i32_16x16x64_i8 v[122:125], v[160:163], v[184:187], v[122:125]
	v_mfma_i32_16x16x64_i8 v[110:113], v[146:149], v[192:195], v[110:113]
	v_mfma_i32_16x16x64_i8 v[106:109], v[160:163], v[192:195], v[106:109]
	v_mfma_i32_16x16x64_i8 v[94:97], v[146:149], v[200:203], v[94:97]
	v_mfma_i32_16x16x64_i8 v[90:93], v[160:163], v[200:203], v[90:93]
	v_mfma_i32_16x16x64_i8 v[78:81], v[146:149], v[208:211], v[78:81]
	v_mfma_i32_16x16x64_i8 v[74:77], v[160:163], v[208:211], v[74:77]
	v_mfma_i32_16x16x64_i8 v[126:129], v[150:153], v[188:191], v[126:129]
	v_mfma_i32_16x16x64_i8 v[122:125], v[164:167], v[188:191], v[122:125]
	v_mfma_i32_16x16x64_i8 v[110:113], v[150:153], v[196:199], v[110:113]
	v_mfma_i32_16x16x64_i8 v[106:109], v[164:167], v[196:199], v[106:109]
	v_mfma_i32_16x16x64_i8 v[94:97], v[150:153], v[204:207], v[94:97]
	v_mfma_i32_16x16x64_i8 v[90:93], v[164:167], v[204:207], v[90:93]
	v_mfma_i32_16x16x64_i8 v[78:81], v[150:153], v[212:215], v[78:81]
	v_mfma_i32_16x16x64_i8 v[74:77], v[164:167], v[212:215], v[74:77]
	s_setprio 0
	s_setprio 1
	v_mfma_i32_16x16x64_i8 v[118:121], v[168:171], v[184:187], v[118:121]
	v_mfma_i32_16x16x64_i8 v[114:117], v[176:179], v[184:187], v[114:117]
	v_mfma_i32_16x16x64_i8 v[102:105], v[168:171], v[192:195], v[102:105]
	v_mfma_i32_16x16x64_i8 v[98:101], v[176:179], v[192:195], v[98:101]
	v_mfma_i32_16x16x64_i8 v[86:89], v[168:171], v[200:203], v[86:89]
	v_mfma_i32_16x16x64_i8 v[82:85], v[176:179], v[200:203], v[82:85]
	v_mfma_i32_16x16x64_i8 v[70:73], v[168:171], v[208:211], v[70:73]
	v_mfma_i32_16x16x64_i8 v[66:69], v[176:179], v[208:211], v[66:69]
	v_mfma_i32_16x16x64_i8 v[118:121], v[172:175], v[188:191], v[118:121]
	v_mfma_i32_16x16x64_i8 v[114:117], v[180:183], v[188:191], v[114:117]
	v_mfma_i32_16x16x64_i8 v[102:105], v[172:175], v[196:199], v[102:105]
	v_mfma_i32_16x16x64_i8 v[98:101], v[180:183], v[196:199], v[98:101]
	v_mfma_i32_16x16x64_i8 v[86:89], v[172:175], v[204:207], v[86:89]
	v_mfma_i32_16x16x64_i8 v[82:85], v[180:183], v[204:207], v[82:85]
	v_mfma_i32_16x16x64_i8 v[70:73], v[172:175], v[212:215], v[70:73]
	v_mfma_i32_16x16x64_i8 v[66:69], v[180:183], v[212:215], v[66:69]
	s_barrier
	s_setprio 0
	s_add_i32 s46, s68, s19
	v_lshl_add_u64 v[216:217], v[216:217], 0, s[4:5]
	s_mov_b32 m0, s46
	ds_read_b128 v[184:187], v158 offset:49152
	ds_read_b128 v[188:191], v158 offset:50176
	ds_read_b128 v[192:195], v158 offset:51200
	ds_read_b128 v[196:199], v158 offset:52224
	ds_read_b128 v[200:203], v158 offset:53248
	ds_read_b128 v[204:207], v158 offset:54272
	ds_read_b128 v[208:211], v158 offset:55296
	ds_read_b128 v[212:215], v158 offset:56320
	global_load_lds_dwordx4 v[216:217], off
	s_add_i32 m0, s46, 0x2000
	s_add_u32 s44, s44, 0x80080
	v_lshl_add_u64 v[216:217], v[218:219], 0, s[4:5]
	s_addc_u32 s45, s45, 0
	s_add_i32 s46, s69, s19
	global_load_lds_dwordx4 v[216:217], off
	v_lshl_add_u64 v[216:217], s[44:45], 0, v[134:135]
	s_mov_b32 m0, s46
	s_nop 0
	global_load_lds_dwordx4 v[216:217], off
	v_lshl_add_u64 v[216:217], s[44:45], 0, v[130:131]
	s_add_i32 m0, s46, 0x2000
	s_nop 0
	global_load_lds_dwordx4 v[216:217], off
	v_lshl_add_u64 v[216:217], v[220:221], 0, s[4:5]
	s_mov_b32 m0, s53
	s_nop 0
	global_load_lds_dwordx4 v[216:217], off
	v_lshl_add_u64 v[216:217], v[222:223], 0, s[4:5]
	s_mov_b32 m0, s54
	s_nop 0
	global_load_lds_dwordx4 v[216:217], off
	s_waitcnt vmcnt(8)
	s_waitcnt lgkmcnt(0)
	s_setprio 1
	s_barrier
	v_mfma_i32_16x16x64_i8 v[62:65], v[146:149], v[184:187], v[62:65]
	v_mfma_i32_16x16x64_i8 v[58:61], v[160:163], v[184:187], v[58:61]
	v_mfma_i32_16x16x64_i8 v[46:49], v[146:149], v[192:195], v[46:49]
	v_mfma_i32_16x16x64_i8 v[42:45], v[160:163], v[192:195], v[42:45]
	v_mfma_i32_16x16x64_i8 v[30:33], v[146:149], v[200:203], v[30:33]
	v_mfma_i32_16x16x64_i8 v[26:29], v[160:163], v[200:203], v[26:29]
	v_mfma_i32_16x16x64_i8 v[14:17], v[146:149], v[208:211], v[14:17]
	v_mfma_i32_16x16x64_i8 v[10:13], v[160:163], v[208:211], v[10:13]
	v_mfma_i32_16x16x64_i8 v[62:65], v[150:153], v[188:191], v[62:65]
	v_mfma_i32_16x16x64_i8 v[58:61], v[164:167], v[188:191], v[58:61]
	v_mfma_i32_16x16x64_i8 v[46:49], v[150:153], v[196:199], v[46:49]
	v_mfma_i32_16x16x64_i8 v[42:45], v[164:167], v[196:199], v[42:45]
	v_mfma_i32_16x16x64_i8 v[30:33], v[150:153], v[204:207], v[30:33]
	v_mfma_i32_16x16x64_i8 v[26:29], v[164:167], v[204:207], v[26:29]
	v_mfma_i32_16x16x64_i8 v[14:17], v[150:153], v[212:215], v[14:17]
	v_mfma_i32_16x16x64_i8 v[10:13], v[164:167], v[212:215], v[10:13]
	s_setprio 0
	s_setprio 1
	v_mfma_i32_16x16x64_i8 v[54:57], v[168:171], v[184:187], v[54:57]
	v_mfma_i32_16x16x64_i8 v[50:53], v[176:179], v[184:187], v[50:53]
	v_mfma_i32_16x16x64_i8 v[38:41], v[168:171], v[192:195], v[38:41]
	v_mfma_i32_16x16x64_i8 v[34:37], v[176:179], v[192:195], v[34:37]
	v_mfma_i32_16x16x64_i8 v[22:25], v[168:171], v[200:203], v[22:25]
	v_mfma_i32_16x16x64_i8 v[18:21], v[176:179], v[200:203], v[18:21]
	v_mfma_i32_16x16x64_i8 v[6:9], v[168:171], v[208:211], v[6:9]
	v_mfma_i32_16x16x64_i8 v[2:5], v[176:179], v[208:211], v[2:5]
	v_mfma_i32_16x16x64_i8 v[54:57], v[172:175], v[188:191], v[54:57]
	v_mfma_i32_16x16x64_i8 v[50:53], v[180:183], v[188:191], v[50:53]
	v_mfma_i32_16x16x64_i8 v[38:41], v[172:175], v[196:199], v[38:41]
	v_mfma_i32_16x16x64_i8 v[34:37], v[180:183], v[196:199], v[34:37]
	v_mfma_i32_16x16x64_i8 v[22:25], v[172:175], v[204:207], v[22:25]
	v_mfma_i32_16x16x64_i8 v[18:21], v[180:183], v[204:207], v[18:21]
	v_mfma_i32_16x16x64_i8 v[6:9], v[172:175], v[212:215], v[6:9]
	v_mfma_i32_16x16x64_i8 v[2:5], v[180:183], v[212:215], v[2:5]
	s_barrier
	s_setprio 0
	s_add_i32 s67, s67, 2
	s_add_u32 s42, s42, 0x100
	s_addc_u32 s43, s43, 0
	s_add_u32 s61, s61, 0x100
	s_addc_u32 s66, s66, 0
	s_cmp_gt_u32 s67, 29
	s_cbranch_scc0 .LBB0_1015
	s_and_b64 vcc, exec, s[12:13]
	s_cbranch_vccz .LBB0_1018
	s_barrier

.LBB0_1166:
	ds_read_b128 v[104:107], v167
	ds_read_b128 v[108:111], v167 offset:1024
	ds_read_b128 v[112:115], v167 offset:2048
	ds_read_b128 v[120:123], v167 offset:3072
	ds_read_b128 v[158:161], v168
	ds_read_b128 v[170:173], v168 offset:1024
	ds_read_b128 v[174:177], v168 offset:2048
	ds_read_b128 v[178:181], v168 offset:3072
	s_add_u32 s26, s6, 0xffea8080
	s_addc_u32 s27, s7, -1
	s_cmpk_eq_i32 s55, 0x52
	s_cselect_b32 s29, s23, s27
	s_cselect_b32 s28, s22, s26
	s_cselect_b32 s27, s25, s9
	s_cselect_b32 s26, s24, s8
	v_lshl_add_u64 v[214:215], s[6:7], 0, v[152:153]
	s_add_i32 m0, s38, 0xc000
	ds_read_b128 v[182:185], v169
	ds_read_b128 v[186:189], v169 offset:1024
	ds_read_b128 v[190:193], v169 offset:2048
	ds_read_b128 v[194:197], v169 offset:3072
	ds_read_b128 v[198:201], v169 offset:4096
	ds_read_b128 v[202:205], v169 offset:5120
	ds_read_b128 v[206:209], v169 offset:6144
	ds_read_b128 v[210:213], v169 offset:7168
	global_load_lds_dwordx4 v[214:215], off
	v_lshl_add_u64 v[214:215], s[6:7], 0, v[154:155]
	s_add_i32 m0, s38, 0xe000
	s_nop 0
	global_load_lds_dwordx4 v[214:215], off
	s_waitcnt vmcnt(8)
	s_waitcnt lgkmcnt(0)
	s_setprio 1
	s_barrier
	v_mfma_i32_16x16x64_i8 v[140:143], v[104:107], v[182:185], v[140:143]
	v_mfma_i32_16x16x64_i8 v[136:139], v[112:115], v[182:185], v[136:139]
	v_mfma_i32_16x16x64_i8 v[124:127], v[104:107], v[190:193], v[124:127]
	v_mfma_i32_16x16x64_i8 v[116:119], v[112:115], v[190:193], v[116:119]
	v_mfma_i32_16x16x64_i8 v[92:95], v[104:107], v[198:201], v[92:95]
	v_mfma_i32_16x16x64_i8 v[88:91], v[112:115], v[198:201], v[88:91]
	v_mfma_i32_16x16x64_i8 v[76:79], v[104:107], v[206:209], v[76:79]
	v_mfma_i32_16x16x64_i8 v[72:75], v[112:115], v[206:209], v[72:75]
	v_mfma_i32_16x16x64_i8 v[140:143], v[108:111], v[186:189], v[140:143]
	v_mfma_i32_16x16x64_i8 v[136:139], v[120:123], v[186:189], v[136:139]
	v_mfma_i32_16x16x64_i8 v[124:127], v[108:111], v[194:197], v[124:127]
	v_mfma_i32_16x16x64_i8 v[116:119], v[120:123], v[194:197], v[116:119]
	v_mfma_i32_16x16x64_i8 v[92:95], v[108:111], v[202:205], v[92:95]
	v_mfma_i32_16x16x64_i8 v[88:91], v[120:123], v[202:205], v[88:91]
	v_mfma_i32_16x16x64_i8 v[76:79], v[108:111], v[210:213], v[76:79]
	v_mfma_i32_16x16x64_i8 v[72:75], v[120:123], v[210:213], v[72:75]
	s_setprio 0
	s_setprio 1
	v_mfma_i32_16x16x64_i8 v[132:135], v[158:161], v[182:185], v[132:135]
	v_mfma_i32_16x16x64_i8 v[128:131], v[174:177], v[182:185], v[128:131]
	v_mfma_i32_16x16x64_i8 v[100:103], v[158:161], v[190:193], v[100:103]
	v_mfma_i32_16x16x64_i8 v[96:99], v[174:177], v[190:193], v[96:99]
	v_mfma_i32_16x16x64_i8 v[84:87], v[158:161], v[198:201], v[84:87]
	v_mfma_i32_16x16x64_i8 v[80:83], v[174:177], v[198:201], v[80:83]
	v_mfma_i32_16x16x64_i8 v[68:71], v[158:161], v[206:209], v[68:71]
	v_mfma_i32_16x16x64_i8 v[64:67], v[174:177], v[206:209], v[64:67]
	v_mfma_i32_16x16x64_i8 v[132:135], v[170:173], v[186:189], v[132:135]
	v_mfma_i32_16x16x64_i8 v[128:131], v[178:181], v[186:189], v[128:131]
	v_mfma_i32_16x16x64_i8 v[100:103], v[170:173], v[194:197], v[100:103]
	v_mfma_i32_16x16x64_i8 v[96:99], v[178:181], v[194:197], v[96:99]
	v_mfma_i32_16x16x64_i8 v[84:87], v[170:173], v[202:205], v[84:87]
	v_mfma_i32_16x16x64_i8 v[80:83], v[178:181], v[202:205], v[80:83]
	v_mfma_i32_16x16x64_i8 v[68:71], v[170:173], v[210:213], v[68:71]
	v_mfma_i32_16x16x64_i8 v[64:67], v[178:181], v[210:213], v[64:67]
	s_barrier
	s_setprio 0
	s_add_i32 s56, s48, s35
	v_lshl_add_u64 v[214:215], s[26:27], 0, v[146:147]
	s_mov_b32 m0, s56
	ds_read_b128 v[182:185], v169 offset:16384
	ds_read_b128 v[186:189], v169 offset:17408
	ds_read_b128 v[190:193], v169 offset:18432
	ds_read_b128 v[194:197], v169 offset:19456
	ds_read_b128 v[198:201], v169 offset:20480
	ds_read_b128 v[202:205], v169 offset:21504
	ds_read_b128 v[206:209], v169 offset:22528
	ds_read_b128 v[210:213], v169 offset:23552
	global_load_lds_dwordx4 v[214:215], off
	s_add_i32 m0, s56, 0x2000
	s_add_u32 s56, s26, 0x158000
	v_lshl_add_u64 v[216:217], s[26:27], 0, v[150:151]
	s_addc_u32 s57, s27, 0
	s_add_i32 s58, s49, s35
	global_load_lds_dwordx4 v[216:217], off
	v_lshl_add_u64 v[218:219], s[56:57], 0, v[146:147]
	s_mov_b32 m0, s58
	v_lshl_add_u64 v[220:221], s[28:29], 0, v[148:149]
	global_load_lds_dwordx4 v[218:219], off
	v_lshl_add_u64 v[218:219], s[56:57], 0, v[150:151]
	s_add_i32 m0, s58, 0x2000
	s_nop 0
	global_load_lds_dwordx4 v[218:219], off
	v_lshl_add_u64 v[218:219], s[28:29], 0, v[144:145]
	s_mov_b32 m0, s38
	s_nop 0
	global_load_lds_dwordx4 v[218:219], off
	s_mov_b32 m0, s39
	s_nop 0
	global_load_lds_dwordx4 v[220:221], off
	s_waitcnt vmcnt(8)
	s_waitcnt lgkmcnt(0)
	s_setprio 1
	s_barrier
	v_mfma_i32_16x16x64_i8 v[60:63], v[104:107], v[182:185], v[60:63]
	v_mfma_i32_16x16x64_i8 v[56:59], v[112:115], v[182:185], v[56:59]
	v_mfma_i32_16x16x64_i8 v[44:47], v[104:107], v[190:193], v[44:47]
	v_mfma_i32_16x16x64_i8 v[40:43], v[112:115], v[190:193], v[40:43]
	v_mfma_i32_16x16x64_i8 v[28:31], v[104:107], v[198:201], v[28:31]
	v_mfma_i32_16x16x64_i8 v[24:27], v[112:115], v[198:201], v[24:27]
	v_mfma_i32_16x16x64_i8 v[12:15], v[104:107], v[206:209], v[12:15]
	v_mfma_i32_16x16x64_i8 v[8:11], v[112:115], v[206:209], v[8:11]
	v_mfma_i32_16x16x64_i8 v[60:63], v[108:111], v[186:189], v[60:63]
	v_mfma_i32_16x16x64_i8 v[56:59], v[120:123], v[186:189], v[56:59]
	v_mfma_i32_16x16x64_i8 v[44:47], v[108:111], v[194:197], v[44:47]
	v_mfma_i32_16x16x64_i8 v[40:43], v[120:123], v[194:197], v[40:43]
	v_mfma_i32_16x16x64_i8 v[28:31], v[108:111], v[202:205], v[28:31]
	v_mfma_i32_16x16x64_i8 v[24:27], v[120:123], v[202:205], v[24:27]
	v_mfma_i32_16x16x64_i8 v[12:15], v[108:111], v[210:213], v[12:15]
	v_mfma_i32_16x16x64_i8 v[8:11], v[120:123], v[210:213], v[8:11]
	s_setprio 0
	s_setprio 1
	v_mfma_i32_16x16x64_i8 v[52:55], v[158:161], v[182:185], v[52:55]
	v_mfma_i32_16x16x64_i8 v[48:51], v[174:177], v[182:185], v[48:51]
	v_mfma_i32_16x16x64_i8 v[36:39], v[158:161], v[190:193], v[36:39]
	v_mfma_i32_16x16x64_i8 v[32:35], v[174:177], v[190:193], v[32:35]
	v_mfma_i32_16x16x64_i8 v[20:23], v[158:161], v[198:201], v[20:23]
	v_mfma_i32_16x16x64_i8 v[16:19], v[174:177], v[198:201], v[16:19]
	v_mfma_i32_16x16x64_i8 v[4:7], v[158:161], v[206:209], v[4:7]
	v_mfma_i32_16x16x64_i8 v[0:3], v[174:177], v[206:209], v[0:3]
	v_mfma_i32_16x16x64_i8 v[52:55], v[170:173], v[186:189], v[52:55]
	v_mfma_i32_16x16x64_i8 v[48:51], v[178:181], v[186:189], v[48:51]
	v_mfma_i32_16x16x64_i8 v[36:39], v[170:173], v[194:197], v[36:39]
	v_mfma_i32_16x16x64_i8 v[32:35], v[178:181], v[194:197], v[32:35]
	v_mfma_i32_16x16x64_i8 v[20:23], v[170:173], v[202:205], v[20:23]
	v_mfma_i32_16x16x64_i8 v[16:19], v[178:181], v[202:205], v[16:19]
	v_mfma_i32_16x16x64_i8 v[4:7], v[170:173], v[210:213], v[4:7]
	v_mfma_i32_16x16x64_i8 v[0:3], v[178:181], v[210:213], v[0:3]
	s_barrier
	s_setprio 0
	s_add_i32 s56, 0, 0x18000
	s_add_i32 s57, 0, 0x1c000
	v_add_u32_e32 v120, s56, v165
	v_add_u32_e32 v162, s57, v165
	ds_read_b128 v[104:107], v120
	ds_read_b128 v[108:111], v120 offset:1024
	ds_read_b128 v[112:115], v120 offset:2048
	ds_read_b128 v[120:123], v120 offset:3072
	ds_read_b128 v[158:161], v162
	ds_read_b128 v[170:173], v162 offset:1024
	ds_read_b128 v[174:177], v162 offset:2048
	ds_read_b128 v[178:181], v162 offset:3072
	s_add_u32 s28, s28, 0x158000
	s_addc_u32 s29, s29, 0
	s_mov_b32 m0, s40
	v_lshl_add_u64 v[222:223], s[28:29], 0, v[144:145]
	ds_read_b128 v[182:185], v169 offset:32768
	ds_read_b128 v[186:189], v169 offset:33792
	ds_read_b128 v[190:193], v169 offset:34816
	ds_read_b128 v[194:197], v169 offset:35840
	ds_read_b128 v[198:201], v169 offset:36864
	ds_read_b128 v[202:205], v169 offset:37888
	ds_read_b128 v[206:209], v169 offset:38912
	ds_read_b128 v[210:213], v169 offset:39936
	global_load_lds_dwordx4 v[222:223], off
	v_lshl_add_u64 v[222:223], s[28:29], 0, v[148:149]
	s_mov_b32 m0, s41
	s_nop 0
	global_load_lds_dwordx4 v[222:223], off
	s_waitcnt vmcnt(8)
	s_waitcnt lgkmcnt(0)
	s_setprio 1
	s_barrier
	v_mfma_i32_16x16x64_i8 v[140:143], v[104:107], v[182:185], v[140:143]
	v_mfma_i32_16x16x64_i8 v[136:139], v[112:115], v[182:185], v[136:139]
	v_mfma_i32_16x16x64_i8 v[124:127], v[104:107], v[190:193], v[124:127]
	v_mfma_i32_16x16x64_i8 v[116:119], v[112:115], v[190:193], v[116:119]
	v_mfma_i32_16x16x64_i8 v[92:95], v[104:107], v[198:201], v[92:95]
	v_mfma_i32_16x16x64_i8 v[88:91], v[112:115], v[198:201], v[88:91]
	v_mfma_i32_16x16x64_i8 v[76:79], v[104:107], v[206:209], v[76:79]
	v_mfma_i32_16x16x64_i8 v[72:75], v[112:115], v[206:209], v[72:75]
	v_mfma_i32_16x16x64_i8 v[140:143], v[108:111], v[186:189], v[140:143]
	v_mfma_i32_16x16x64_i8 v[136:139], v[120:123], v[186:189], v[136:139]
	v_mfma_i32_16x16x64_i8 v[124:127], v[108:111], v[194:197], v[124:127]
	v_mfma_i32_16x16x64_i8 v[116:119], v[120:123], v[194:197], v[116:119]
	v_mfma_i32_16x16x64_i8 v[92:95], v[108:111], v[202:205], v[92:95]
	v_mfma_i32_16x16x64_i8 v[88:91], v[120:123], v[202:205], v[88:91]
	v_mfma_i32_16x16x64_i8 v[76:79], v[108:111], v[210:213], v[76:79]
	v_mfma_i32_16x16x64_i8 v[72:75], v[120:123], v[210:213], v[72:75]
	s_setprio 0
	s_setprio 1
	v_mfma_i32_16x16x64_i8 v[132:135], v[158:161], v[182:185], v[132:135]
	v_mfma_i32_16x16x64_i8 v[128:131], v[174:177], v[182:185], v[128:131]
	v_mfma_i32_16x16x64_i8 v[100:103], v[158:161], v[190:193], v[100:103]
	v_mfma_i32_16x16x64_i8 v[96:99], v[174:177], v[190:193], v[96:99]
	v_mfma_i32_16x16x64_i8 v[84:87], v[158:161], v[198:201], v[84:87]
	v_mfma_i32_16x16x64_i8 v[80:83], v[174:177], v[198:201], v[80:83]
	v_mfma_i32_16x16x64_i8 v[68:71], v[158:161], v[206:209], v[68:71]
	v_mfma_i32_16x16x64_i8 v[64:67], v[174:177], v[206:209], v[64:67]
	v_mfma_i32_16x16x64_i8 v[132:135], v[170:173], v[186:189], v[132:135]
	v_mfma_i32_16x16x64_i8 v[128:131], v[178:181], v[186:189], v[128:131]
	v_mfma_i32_16x16x64_i8 v[100:103], v[170:173], v[194:197], v[100:103]
	v_mfma_i32_16x16x64_i8 v[96:99], v[178:181], v[194:197], v[96:99]
	v_mfma_i32_16x16x64_i8 v[84:87], v[170:173], v[202:205], v[84:87]
	v_mfma_i32_16x16x64_i8 v[80:83], v[178:181], v[202:205], v[80:83]
	v_mfma_i32_16x16x64_i8 v[68:71], v[170:173], v[210:213], v[68:71]
	v_mfma_i32_16x16x64_i8 v[64:67], v[178:181], v[210:213], v[64:67]
	s_barrier
	s_setprio 0
	s_add_i32 s28, s56, s35
	v_lshl_add_u64 v[214:215], v[214:215], 0, s[16:17]
	s_mov_b32 m0, s28
	ds_read_b128 v[182:185], v169 offset:49152
	ds_read_b128 v[186:189], v169 offset:50176
	ds_read_b128 v[190:193], v169 offset:51200
	ds_read_b128 v[194:197], v169 offset:52224
	ds_read_b128 v[198:201], v169 offset:53248
	ds_read_b128 v[202:205], v169 offset:54272
	ds_read_b128 v[206:209], v169 offset:55296
	ds_read_b128 v[210:213], v169 offset:56320
	global_load_lds_dwordx4 v[214:215], off
	s_add_i32 m0, s28, 0x2000
	s_add_u32 s26, s26, 0x158080
	v_lshl_add_u64 v[214:215], v[216:217], 0, s[16:17]
	s_addc_u32 s27, s27, 0
	s_add_i32 s28, s57, s35
	global_load_lds_dwordx4 v[214:215], off
	v_lshl_add_u64 v[214:215], s[26:27], 0, v[146:147]
	s_mov_b32 m0, s28
	s_nop 0
	global_load_lds_dwordx4 v[214:215], off
	v_lshl_add_u64 v[214:215], s[26:27], 0, v[150:151]
	s_add_i32 m0, s28, 0x2000
	s_nop 0
	global_load_lds_dwordx4 v[214:215], off
	v_lshl_add_u64 v[214:215], v[218:219], 0, s[16:17]
	s_mov_b32 m0, s42
	s_nop 0
	global_load_lds_dwordx4 v[214:215], off
	v_lshl_add_u64 v[214:215], v[220:221], 0, s[16:17]
	s_mov_b32 m0, s43
	s_nop 0
	global_load_lds_dwordx4 v[214:215], off
	s_waitcnt vmcnt(8)
	s_waitcnt lgkmcnt(0)
	s_setprio 1
	s_barrier
	v_mfma_i32_16x16x64_i8 v[60:63], v[104:107], v[182:185], v[60:63]
	v_mfma_i32_16x16x64_i8 v[56:59], v[112:115], v[182:185], v[56:59]
	v_mfma_i32_16x16x64_i8 v[44:47], v[104:107], v[190:193], v[44:47]
	v_mfma_i32_16x16x64_i8 v[40:43], v[112:115], v[190:193], v[40:43]
	v_mfma_i32_16x16x64_i8 v[28:31], v[104:107], v[198:201], v[28:31]
	v_mfma_i32_16x16x64_i8 v[24:27], v[112:115], v[198:201], v[24:27]
	v_mfma_i32_16x16x64_i8 v[12:15], v[104:107], v[206:209], v[12:15]
	v_mfma_i32_16x16x64_i8 v[8:11], v[112:115], v[206:209], v[8:11]
	v_mfma_i32_16x16x64_i8 v[60:63], v[108:111], v[186:189], v[60:63]
	v_mfma_i32_16x16x64_i8 v[56:59], v[120:123], v[186:189], v[56:59]
	v_mfma_i32_16x16x64_i8 v[44:47], v[108:111], v[194:197], v[44:47]
	v_mfma_i32_16x16x64_i8 v[40:43], v[120:123], v[194:197], v[40:43]
	v_mfma_i32_16x16x64_i8 v[28:31], v[108:111], v[202:205], v[28:31]
	v_mfma_i32_16x16x64_i8 v[24:27], v[120:123], v[202:205], v[24:27]
	v_mfma_i32_16x16x64_i8 v[12:15], v[108:111], v[210:213], v[12:15]
	v_mfma_i32_16x16x64_i8 v[8:11], v[120:123], v[210:213], v[8:11]
	s_setprio 0
	s_setprio 1
	v_mfma_i32_16x16x64_i8 v[52:55], v[158:161], v[182:185], v[52:55]
	v_mfma_i32_16x16x64_i8 v[48:51], v[174:177], v[182:185], v[48:51]
	v_mfma_i32_16x16x64_i8 v[36:39], v[158:161], v[190:193], v[36:39]
	v_mfma_i32_16x16x64_i8 v[32:35], v[174:177], v[190:193], v[32:35]
	v_mfma_i32_16x16x64_i8 v[20:23], v[158:161], v[198:201], v[20:23]
	v_mfma_i32_16x16x64_i8 v[16:19], v[174:177], v[198:201], v[16:19]
	v_mfma_i32_16x16x64_i8 v[4:7], v[158:161], v[206:209], v[4:7]
	v_mfma_i32_16x16x64_i8 v[0:3], v[174:177], v[206:209], v[0:3]
	v_mfma_i32_16x16x64_i8 v[52:55], v[170:173], v[186:189], v[52:55]
	v_mfma_i32_16x16x64_i8 v[48:51], v[178:181], v[186:189], v[48:51]
	v_mfma_i32_16x16x64_i8 v[36:39], v[170:173], v[194:197], v[36:39]
	v_mfma_i32_16x16x64_i8 v[32:35], v[178:181], v[194:197], v[32:35]
	v_mfma_i32_16x16x64_i8 v[20:23], v[170:173], v[202:205], v[20:23]
	v_mfma_i32_16x16x64_i8 v[16:19], v[178:181], v[202:205], v[16:19]
	v_mfma_i32_16x16x64_i8 v[4:7], v[170:173], v[210:213], v[4:7]
	v_mfma_i32_16x16x64_i8 v[0:3], v[178:181], v[210:213], v[0:3]
	s_barrier
	s_setprio 0
	s_add_i32 s55, s55, 2
	s_add_u32 s6, s6, 0x100
	s_addc_u32 s7, s7, 0
	s_add_u32 s8, s8, 0x100
	s_addc_u32 s9, s9, 0
	s_cmpk_gt_u32 s55, 0x53
	s_cbranch_scc0 .LBB0_1166
	s_and_b64 vcc, exec, s[18:19]
	s_cbranch_vccz .LBB0_1169
	s_barrier
